# one static s_setprio 1 for waves 4-7 (lagging half) per GEMM phase, all per-segment flips deleted
# baseline (speedup 1.0000x reference)
; __device__ __forceinline__ int tid_fresh() { int t = threadIdx.x; asm volatile("" : "+v"(t)); return t; }
; #define PG8_STAGE(bufoff, gbase, voff) do { _Pragma("unroll") for (int _i = 0; _i < 2; ++_i) \
;         __builtin_amdgcn_global_load_lds((const unsigned*)((const char*)(gbase) + (voff)[_i]), (LAS unsigned*)(lds + (bufoff) + ldsw + _i * 8192), 16, 0, 0); } while (0)
; #define PG8_WAIT_V(n) asm volatile("s_waitcnt vmcnt(" #n ")" ::: "memory")
; #define PG8_BAR __builtin_amdgcn_s_barrier()
; template <class Epi, class Sched, bool ABLK = false, bool ALIGN_EPI = true, bool SP2 = true, bool BBLK = true>
; __device__ __forceinline__ void gemm_phase(LAS unsigned char* lds, const Gemm g, const Sched& S, const Epi& E) {
;     const int tid = tid_fresh(), wid = __builtin_amdgcn_readfirstlane(tid >> 6), lane = tid & 63, wr = wid >> 2, wc = wid & 3, fr = lane & 15, fq = lane >> 4;
;     unsigned voffA[2], voffB[2];
; #pragma unroll
;     for (int i = 0; i < 2; ++i) { int R, C; stage_rc(tid * 16 + i * 8192, R, C); const int r32 = Epi::PERM ? perm32(R & 31) : (R & 31);
;         const int Rb = Epi::ADJ ? 64 * (R >> 5) + r32 : (R & ~31) + r32;
;         voffA[i] = (unsigned)(R * (ABLK ? 64 : g.lda) + C) * 2u; voffB[i] = BBLK ? (unsigned)(R * 64 + C) * 2u : (unsigned)(Rb * g.ldb + C) * 2u; }
;     ...
;     const char* uA = a_unit(cur); int tbA = cur.k0 / BK;
;     const char* cA = a_tile(uA, tbA); const char* cB = (const char*)g.Bt + (size_t)cur.pn * tstepB + b_k0(cur.k0);
;     S.a_ready(cur);
;     if constexpr (SP2) {
;         PG8_STAGE(PG8_SB(0, 0), cB, voffB); PG8_STAGE(PG8_SB(0, 1), cB + hstepB, voffB); PG8_STAGE(PG8_SA(0, 0), cA, voffA); PG8_STAGE(PG8_SA(0, 1), cA + hstepA, voffA);
;         if (wr == 1) PG8_BAR;
;         PG8_WAIT_V(2); PG8_BAR;
;         PG8_STAGE(PG8_SB(1, 0), cB + kstepB, voffB); PG8_STAGE(PG8_SA(1, 0), a_tile(uA, tbA + 1), voffA); PG8_STAGE(PG8_SB(1, 1), cB + hstepB + kstepB, voffB);
;         PG8_WAIT_V(6); PG8_BAR;
;     } else {
;         PG8_STAGE(PG8_SB(0, 0), cB, voffB); PG8_STAGE(PG8_SA(0, 0), cA, voffA); PG8_STAGE(PG8_SB(0, 1), cB + hstepB, voffB); PG8_STAGE(PG8_SA(0, 1), cA + hstepA, voffA);
;         if (wr == 1) PG8_BAR;
.LBB0_341:
	s_or_b64 exec, exec, s[2:3]
	s_add_u32 s16, s68, 0x1e100000
	s_addc_u32 s17, s69, 0
	s_and_b32 s91, s90, 7
	s_ashr_i32 s70, s90, 3
	s_cmpk_lt_i32 s70, 0x50
	s_waitcnt vmcnt(22)
	v_mov_b32_e32 v6, v0
	s_cselect_b64 s[0:1], -1, 0
	s_waitcnt lgkmcnt(0)
	s_barrier
	v_writelane_b32 v252, s0, 12
	s_cmpk_gt_i32 s70, 0x4f
	v_readfirstlane_b32 s4, v6
	v_writelane_b32 v252, s1, 13
	s_cbranch_scc1 .LBB0_357
	v_lshlrev_b32_e32 v1, 4, v6
	v_add_u32_e32 v2, 0x2000, v1
	v_ashrrev_i32_e32 v3, 31, v2
	v_lshrrev_b32_e32 v3, 22, v3
	v_add_u32_e32 v3, v2, v3
	v_ashrrev_i32_e32 v7, 10, v3
	v_mul_i32_i24_e32 v4, 0x400, v7
	v_sub_u32_e32 v2, v2, v4
	v_lshrrev_b32_e32 v4, 4, v2
	v_bitop3_b32 v2, v4, v2, 32 bitop3:0x6c
	v_ashrrev_i32_e32 v4, 31, v2
	v_lshrrev_b32_e32 v4, 26, v4
	v_add_u32_e32 v4, v2, v4
	v_ashrrev_i32_e32 v8, 6, v4
	v_and_b32_e32 v4, 0xc0, v4
	v_sub_u32_e32 v2, v2, v4
	v_mov_b32_e32 v4, 1
	v_lshlrev_b32_e32 v3, 5, v7
	v_ashrrev_i16_sdwa v2, v4, sext(v2) dst_sel:DWORD dst_unused:UNUSED_PAD src0_sel:DWORD src1_sel:BYTE_0
	v_and_b32_e32 v3, 32, v3
	v_bfe_i32 v9, v2, 0, 16
	v_add_u32_e32 v2, v3, v9
	v_lshlrev_b32_e32 v3, 3, v7
	v_and_b32_e32 v3, -16, v3
	v_add_u32_e32 v3, v8, v3
	v_lshlrev_b32_e32 v5, 7, v3
	v_lshl_add_u32 v130, v2, 1, v5
	s_movk_i32 s7, 0xf80
	v_mad_u64_u32 v[132:133], s[2:3], v3, s7, v[130:131]
	v_bfe_i32 v3, v6, 27, 1
	v_lshrrev_b32_e32 v3, 22, v3
	v_add_u32_e32 v3, v1, v3
	v_and_b32_e32 v3, 0xfffffc00, v3
	v_sub_u32_e32 v1, v1, v3
	v_lshrrev_b32_e32 v3, 4, v1
	v_bitop3_b32 v3, v3, v1, 32 bitop3:0x6c
	v_ashrrev_i32_e32 v1, 31, v1
	v_lshrrev_b32_e32 v1, 26, v1
	v_ashrrev_i32_e32 v2, 31, v6
	v_add_u32_e32 v1, v3, v1
	v_lshrrev_b32_e32 v2, 26, v2
	s_waitcnt vmcnt(21)
	v_ashrrev_i32_e32 v11, 6, v1
	v_add_u32_e32 v2, v6, v2
	v_mul_i32_i24_e32 v1, 64, v11
	v_ashrrev_i32_e32 v10, 6, v2
	v_sub_u32_e32 v1, v3, v1
	v_lshlrev_b32_e32 v2, 5, v10
	v_ashrrev_i16_sdwa v1, v4, sext(v1) dst_sel:DWORD dst_unused:UNUSED_PAD src0_sel:DWORD src1_sel:BYTE_0
	v_and_b32_e32 v2, 32, v2
	v_bfe_i32 v12, v1, 0, 16
	v_add_u32_e32 v1, v2, v12
	v_lshlrev_b32_e32 v2, 3, v10
	v_and_b32_e32 v2, -16, v2
	s_add_u32 s0, s68, 0x100000
	v_add_u32_e32 v2, v11, v2
	s_addc_u32 s1, s69, 0
	s_ashr_i32 s6, s4, 6
	v_lshlrev_b32_e32 v3, 7, v2
	s_ashr_i32 s5, s4, 8
	s_lshl_b32 s33, s6, 10
	v_lshl_add_u32 v134, v1, 1, v3
	s_add_u32 s36, s68, 0x2d100000
	v_mad_u64_u32 v[136:137], s[2:3], v2, s7, v[134:135]
	s_addc_u32 s37, s69, 0
	s_lshr_b32 s2, s70, 31
	s_add_i32 s2, s70, s2
	s_ashr_i32 s20, s2, 1
	s_sub_i32 s2, s91, s20
	s_lshl_b32 s2, s2, 1
	s_add_i32 s22, s2, s70
	s_ashr_i32 s21, s20, 31
	s_ashr_i32 s23, s22, 31
	s_lshl_b64 s[2:3], s[20:21], 20
	s_lshl_b64 s[8:9], s[22:23], 20
	s_add_u32 s26, s0, s8
	s_addc_u32 s27, s1, s9
	s_add_i32 s21, s33, 0
	s_add_i32 m0, s21, 0x10000
	v_mov_b32_e32 v135, 0
	global_load_lds_dwordx4 v134, s[26:27]
	s_add_i32 m0, s21, 0x12000
	s_add_u32 s8, s26, 0x4000
	global_load_lds_dwordx4 v130, s[26:27]
	s_addc_u32 s9, s27, 0
	s_add_i32 m0, s21, 0x14000
	v_mov_b32_e32 v137, v135
	global_load_lds_dwordx4 v134, s[8:9]
	s_add_i32 m0, s21, 0x16000
	s_add_u32 s24, s36, s2
	s_addc_u32 s25, s37, s3
	s_add_i32 s23, s21, 0x2000
	global_load_lds_dwordx4 v130, s[8:9]
	s_mov_b32 m0, s21
	s_add_u32 s2, s24, 0x80000
	global_load_lds_dwordx4 v136, s[24:25]
	s_mov_b32 m0, s23
	s_addc_u32 s3, s25, 0
	s_add_i32 s39, s21, 0x4000
	global_load_lds_dwordx4 v132, s[24:25]
	s_mov_b32 m0, s39
	s_add_i32 s40, s21, 0x6000
	global_load_lds_dwordx4 v136, s[2:3]
	s_mov_b32 m0, s40
	v_mov_b32_e32 v133, v135
	global_load_lds_dwordx4 v132, s[2:3]
	s_cmp_eq_u32 s5, 1
	s_mov_b32 s41, 0
	v_mov_b32_e32 v131, v135
	v_lshl_add_u64 v[2:3], s[24:25], 0, v[136:137]
	s_cselect_b64 s[2:3], -1, 0
	s_cmp_lg_u32 s5, 1
	v_lshl_add_u64 v[4:5], s[24:25], 0, v[132:133]
	s_cbranch_scc1 .LBB0_344
	s_setprio 1
	s_barrier

; #define PG8_WAIT_V(n) asm volatile("s_waitcnt vmcnt(" #n ")" ::: "memory")
; #define PG8_BAR __builtin_amdgcn_s_barrier()
; __device__ __forceinline__ unsigned xb_add(unsigned* p, unsigned v) { return __hip_atomic_fetch_add(p, v, __ATOMIC_RELAXED, __HIP_MEMORY_SCOPE_AGENT); }
; template <class Epi, class Sched, bool ABLK = false, bool ALIGN_EPI = true, bool SP2 = true, bool BBLK = true>
; __device__ __forceinline__ void gemm_phase(LAS unsigned char* lds, const Gemm g, const Sched& S, const Epi& E) {
;     ...
;     PG8_WAIT_V(0);
;     if constexpr (!ALIGN_EPI) { if (wr == 0) PG8_BAR; }
;     PG8_BAR;
; __device__ __forceinline__ void xcd_barrier(const XcdBarrier& b) {
;     asm volatile("s_waitcnt vmcnt(0)" ::: "memory");
;     __syncthreads();
;     if (threadIdx.x == 0) {
;         unsigned* bar = b.bar;
;         __builtin_amdgcn_s_waitcnt(0);
;         unsigned nloc = b.st[0], nx = b.st[1];
;         if (nloc == 0u) { xcd_barrier_complete(bar, b.x, nloc, nx); b.st[0] = nloc; b.st[1] = nx; }
;         const unsigned old = xb_add(&bar[XB_XSUB(b.x)], 1u);
;         const unsigned gen = old / nloc;
.LBB0_357:
	s_waitcnt vmcnt(0)
	s_waitcnt vmcnt(0)
	s_setprio 0
	s_barrier
	s_and_saveexec_b64 s[2:3], s[92:93]
	s_cbranch_execz .LBB0_409
	s_add_i32 s0, 0, 0x20000
	v_mov_b32_e32 v1, s0
	s_waitcnt vmcnt(0) expcnt(0) lgkmcnt(0)
	ds_read_b32 v3, v1
	s_add_i32 s0, 0, 0x20004
	v_mov_b32_e32 v1, s0
	ds_read_b32 v1, v1
	s_waitcnt lgkmcnt(1)
	v_cmp_ne_u32_e32 vcc, 0, v3
	s_cbranch_vccnz .LBB0_373
	s_add_u32 s6, s68, 0x4200
	s_addc_u32 s7, s69, 0
	s_add_u32 s8, s68, 0x4400
	s_addc_u32 s9, s69, 0
	s_add_u32 s10, s68, 0x4500
	s_addc_u32 s11, s69, 0
	s_add_u32 s12, s68, 0x4600
	s_addc_u32 s13, s69, 0
	s_add_u32 s14, s68, 0x4700
	s_addc_u32 s15, s69, 0
	s_add_u32 s18, s68, 0x4800
	s_addc_u32 s19, s69, 0
	s_add_u32 s20, s68, 0x4900
	s_addc_u32 s21, s69, 0
	s_add_u32 s22, s68, 0x4a00
	s_addc_u32 s23, s69, 0
	v_readlane_b32 s4, v252, 7
	s_add_u32 s24, s68, 0x4b00
	v_readlane_b32 s5, v252, 8
	s_addc_u32 s25, s69, 0
	s_load_dwordx2 s[0:1], s[4:5], 0x4
	s_add_u32 s4, s68, 0x4c00
	s_addc_u32 s5, s69, 0
	s_add_u32 s26, s68, 0x4d00
	s_addc_u32 s27, s69, 0
	s_add_u32 s28, s68, 0x4e00
	s_addc_u32 s29, s69, 0
	s_add_u32 s30, s68, 0x4f00
	s_addc_u32 s31, s69, 0
	s_add_u32 s34, s68, 0x5000
	s_addc_u32 s35, s69, 0
	s_add_u32 s36, s68, 0x5100
	s_addc_u32 s37, s69, 0
	s_add_u32 s40, s68, 0x5200
	s_addc_u32 s41, s69, 0
	s_waitcnt lgkmcnt(0)
	s_mul_i32 s0, s0, s89
	s_add_u32 s42, s68, 0x5300
	s_mul_i32 s0, s0, s1
	s_addc_u32 s43, s69, 0
	s_mov_b32 s1, 1
	v_mov_b32_e32 v17, 0
	s_branch .LBB0_361

; __device__ __forceinline__ int tid_fresh() { int t = threadIdx.x; asm volatile("" : "+v"(t)); return t; }
; #define PG8_STAGE(bufoff, gbase, voff) do { _Pragma("unroll") for (int _i = 0; _i < 2; ++_i) \
;         __builtin_amdgcn_global_load_lds((const unsigned*)((const char*)(gbase) + (voff)[_i]), (LAS unsigned*)(lds + (bufoff) + ldsw + _i * 8192), 16, 0, 0); } while (0)
; #define PG8_WAIT_V(n) asm volatile("s_waitcnt vmcnt(" #n ")" ::: "memory")
; #define PG8_BAR __builtin_amdgcn_s_barrier()
; template <class Epi, class Sched, bool ABLK = false, bool ALIGN_EPI = true, bool SP2 = true, bool BBLK = true>
; __device__ __forceinline__ void gemm_phase(LAS unsigned char* lds, const Gemm g, const Sched& S, const Epi& E) {
;     const int tid = tid_fresh(), wid = __builtin_amdgcn_readfirstlane(tid >> 6), lane = tid & 63, wr = wid >> 2, wc = wid & 3, fr = lane & 15, fq = lane >> 4;
;     unsigned voffA[2], voffB[2];
; #pragma unroll
;     for (int i = 0; i < 2; ++i) { int R, C; stage_rc(tid * 16 + i * 8192, R, C); const int r32 = Epi::PERM ? perm32(R & 31) : (R & 31);
;         const int Rb = Epi::ADJ ? 64 * (R >> 5) + r32 : (R & ~31) + r32;
;         voffA[i] = (unsigned)(R * (ABLK ? 64 : g.lda) + C) * 2u; voffB[i] = BBLK ? (unsigned)(R * 64 + C) * 2u : (unsigned)(Rb * g.ldb + C) * 2u; }
;     ...
;     const char* uA = a_unit(cur); int tbA = cur.k0 / BK;
;     const char* cA = a_tile(uA, tbA); const char* cB = (const char*)g.Bt + (size_t)cur.pn * tstepB + b_k0(cur.k0);
;     S.a_ready(cur);
;     if constexpr (SP2) {
;         PG8_STAGE(PG8_SB(0, 0), cB, voffB); PG8_STAGE(PG8_SB(0, 1), cB + hstepB, voffB); PG8_STAGE(PG8_SA(0, 0), cA, voffA); PG8_STAGE(PG8_SA(0, 1), cA + hstepA, voffA);
;         if (wr == 1) PG8_BAR;
;         PG8_WAIT_V(2); PG8_BAR;
;         PG8_STAGE(PG8_SB(1, 0), cB + kstepB, voffB); PG8_STAGE(PG8_SA(1, 0), a_tile(uA, tbA + 1), voffA); PG8_STAGE(PG8_SB(1, 1), cB + hstepB + kstepB, voffB);
;         PG8_WAIT_V(6); PG8_BAR;
;     } else {
;         PG8_STAGE(PG8_SB(0, 0), cB, voffB); PG8_STAGE(PG8_SA(0, 0), cA, voffA); PG8_STAGE(PG8_SB(0, 1), cB + hstepB, voffB); PG8_STAGE(PG8_SA(0, 1), cA + hstepA, voffA);
;         if (wr == 1) PG8_BAR;
.LBB0_466:
	s_or_b64 exec, exec, s[2:3]
	s_add_u32 s1, s68, 0x23100000
	s_addc_u32 s33, s69, 0
	s_cmpk_lt_i32 s70, 0xa0
	s_waitcnt lgkmcnt(0)
	v_mov_b32_e32 v1, v0
	s_cselect_b64 s[2:3], -1, 0
	s_barrier
	v_writelane_b32 v252, s2, 14
	s_cmpk_gt_i32 s70, 0x9f
	v_readfirstlane_b32 s6, v1
	v_writelane_b32 v252, s3, 15
	s_cbranch_scc1 .LBB0_482
	v_lshlrev_b32_e32 v2, 4, v1
	v_add_u32_e32 v3, 0x2000, v2
	v_ashrrev_i32_e32 v4, 31, v3
	v_lshrrev_b32_e32 v4, 22, v4
	v_add_u32_e32 v4, v3, v4
	v_ashrrev_i32_e32 v6, 10, v4
	v_mul_i32_i24_e32 v5, 0x400, v6
	v_sub_u32_e32 v3, v3, v5
	v_lshrrev_b32_e32 v5, 4, v3
	v_bitop3_b32 v3, v5, v3, 32 bitop3:0x6c
	v_ashrrev_i32_e32 v5, 31, v3
	v_lshrrev_b32_e32 v5, 26, v5
	v_add_u32_e32 v5, v3, v5
	v_ashrrev_i32_e32 v7, 6, v5
	v_and_b32_e32 v5, 0xc0, v5
	v_sub_u32_e32 v3, v3, v5
	v_mov_b32_e32 v5, 1
	v_lshlrev_b32_e32 v4, 5, v6
	v_ashrrev_i16_sdwa v3, v5, sext(v3) dst_sel:DWORD dst_unused:UNUSED_PAD src0_sel:DWORD src1_sel:BYTE_0
	v_and_b32_e32 v4, 32, v4
	v_bfe_i32 v8, v3, 0, 16
	v_add_u32_e32 v3, v4, v8
	v_lshlrev_b32_e32 v4, 3, v6
	v_and_b32_e32 v4, -16, v4
	v_add_u32_e32 v4, v7, v4
	v_lshlrev_b32_e32 v9, 7, v4
	v_lshl_add_u32 v130, v3, 1, v9
	s_movk_i32 s4, 0xf80
	v_mad_u64_u32 v[132:133], s[2:3], v4, s4, v[130:131]
	v_bfe_i32 v4, v1, 27, 1
	v_lshrrev_b32_e32 v4, 22, v4
	v_add_u32_e32 v4, v2, v4
	v_and_b32_e32 v4, 0xfffffc00, v4
	v_sub_u32_e32 v2, v2, v4
	v_lshrrev_b32_e32 v4, 4, v2
	v_bitop3_b32 v4, v4, v2, 32 bitop3:0x6c
	v_ashrrev_i32_e32 v2, 31, v2
	v_lshrrev_b32_e32 v2, 26, v2
	v_ashrrev_i32_e32 v3, 31, v1
	v_add_u32_e32 v2, v4, v2
	v_lshrrev_b32_e32 v3, 26, v3
	v_ashrrev_i32_e32 v10, 6, v2
	v_add_u32_e32 v3, v1, v3
	v_mul_i32_i24_e32 v2, 64, v10
	v_ashrrev_i32_e32 v9, 6, v3
	v_sub_u32_e32 v2, v4, v2
	v_lshlrev_b32_e32 v3, 5, v9
	v_ashrrev_i16_sdwa v2, v5, sext(v2) dst_sel:DWORD dst_unused:UNUSED_PAD src0_sel:DWORD src1_sel:BYTE_0
	v_and_b32_e32 v3, 32, v3
	v_bfe_i32 v11, v2, 0, 16
	v_add_u32_e32 v2, v3, v11
	v_lshlrev_b32_e32 v3, 3, v9
	v_and_b32_e32 v3, -16, v3
	s_add_u32 s0, s68, 0x6900000
	v_add_u32_e32 v3, v10, v3
	s_addc_u32 s39, s69, 0
	s_ashr_i32 s8, s6, 6
	v_lshlrev_b32_e32 v4, 7, v3
	s_ashr_i32 s7, s6, 8
	s_lshl_b32 s40, s8, 10
	v_lshl_add_u32 v134, v2, 1, v4
	s_add_u32 s41, s68, 0x1b900000
	v_mad_u64_u32 v[136:137], s[2:3], v3, s4, v[134:135]
	s_addc_u32 s42, s69, 0
	s_lshr_b32 s2, s70, 30
	s_add_i32 s2, s70, s2
	s_ashr_i32 s22, s2, 2
	s_sub_i32 s2, s91, s22
	s_lshl_b32 s2, s2, 2
	s_add_i32 s24, s2, s70
	s_ashr_i32 s23, s22, 31
	s_ashr_i32 s25, s24, 31
	s_lshl_b64 s[2:3], s[22:23], 20
	s_lshl_b64 s[4:5], s[24:25], 20
	s_add_u32 s28, s0, s4
	s_addc_u32 s29, s39, s5
	s_add_i32 s25, s40, 0
	s_add_i32 m0, s25, 0x10000
	v_mov_b32_e32 v139, 0
	global_load_lds_dwordx4 v134, s[28:29]
	s_add_i32 m0, s25, 0x12000
	s_add_u32 s4, s28, 0x4000
	global_load_lds_dwordx4 v130, s[28:29]
	s_addc_u32 s5, s29, 0
	s_add_i32 m0, s25, 0x14000
	v_mov_b32_e32 v137, v139
	global_load_lds_dwordx4 v134, s[4:5]
	s_add_i32 m0, s25, 0x16000
	s_add_u32 s26, s41, s2
	s_addc_u32 s27, s42, s3
	s_add_i32 s43, s25, 0x2000
	global_load_lds_dwordx4 v130, s[4:5]
	s_mov_b32 m0, s25
	s_add_u32 s2, s26, 0x80000
	global_load_lds_dwordx4 v136, s[26:27]
	s_mov_b32 m0, s43
	s_addc_u32 s3, s27, 0
	s_add_i32 s46, s25, 0x4000
	global_load_lds_dwordx4 v132, s[26:27]
	s_mov_b32 m0, s46
	s_add_i32 s47, s25, 0x6000
	global_load_lds_dwordx4 v136, s[2:3]
	s_mov_b32 m0, s47
	v_mov_b32_e32 v133, v139
	global_load_lds_dwordx4 v132, s[2:3]
	s_cmp_eq_u32 s7, 1
	s_mov_b32 s48, 0
	v_mov_b32_e32 v135, v139
	v_mov_b32_e32 v131, v139
	s_mov_b64 s[4:5], 0x4000
	v_lshl_add_u64 v[2:3], s[26:27], 0, v[136:137]
	s_cselect_b64 s[2:3], -1, 0
	s_cmp_lg_u32 s7, 1
	v_lshl_add_u64 v[4:5], s[26:27], 0, v[132:133]
	s_cbranch_scc1 .LBB0_469
	s_setprio 1
	s_barrier

; #define PG8_WAIT_V(n) asm volatile("s_waitcnt vmcnt(" #n ")" ::: "memory")
; #define PG8_BAR __builtin_amdgcn_s_barrier()
; __device__ __forceinline__ unsigned xb_add(unsigned* p, unsigned v) { return __hip_atomic_fetch_add(p, v, __ATOMIC_RELAXED, __HIP_MEMORY_SCOPE_AGENT); }
; template <class Epi, class Sched, bool ABLK = false, bool ALIGN_EPI = true, bool SP2 = true, bool BBLK = true>
; __device__ __forceinline__ void gemm_phase(LAS unsigned char* lds, const Gemm g, const Sched& S, const Epi& E) {
;     ...
;     PG8_WAIT_V(0);
;     if constexpr (!ALIGN_EPI) { if (wr == 0) PG8_BAR; }
;     PG8_BAR;
; __device__ __forceinline__ void xcd_barrier(const XcdBarrier& b) {
;     asm volatile("s_waitcnt vmcnt(0)" ::: "memory");
;     __syncthreads();
;     if (threadIdx.x == 0) {
;         unsigned* bar = b.bar;
;         __builtin_amdgcn_s_waitcnt(0);
;         unsigned nloc = b.st[0], nx = b.st[1];
;         if (nloc == 0u) { xcd_barrier_complete(bar, b.x, nloc, nx); b.st[0] = nloc; b.st[1] = nx; }
;         const unsigned old = xb_add(&bar[XB_XSUB(b.x)], 1u);
;         const unsigned gen = old / nloc;
.LBB0_482:
	s_waitcnt vmcnt(0)
	s_waitcnt vmcnt(0)
	s_setprio 0
	s_barrier
	s_and_saveexec_b64 s[2:3], s[92:93]
	s_cbranch_execz .LBB0_534
	s_add_i32 s0, 0, 0x20000
	v_mov_b32_e32 v1, s0
	s_waitcnt vmcnt(0) expcnt(0) lgkmcnt(0)
	ds_read_b32 v3, v1
	s_add_i32 s0, 0, 0x20004
	v_mov_b32_e32 v1, s0
	ds_read_b32 v1, v1
	s_waitcnt lgkmcnt(1)
	v_cmp_ne_u32_e32 vcc, 0, v3
	s_cbranch_vccnz .LBB0_498
	v_readlane_b32 s6, v252, 7
	v_readlane_b32 s7, v252, 8
	s_load_dwordx2 s[4:5], s[6:7], 0x4
	s_add_u32 s6, s68, 0x4200
	s_addc_u32 s7, s69, 0
	s_add_u32 s8, s68, 0x4400
	s_addc_u32 s9, s69, 0
	s_add_u32 s10, s68, 0x4500
	s_addc_u32 s11, s69, 0
	s_add_u32 s12, s68, 0x4600
	s_addc_u32 s13, s69, 0
	s_add_u32 s14, s68, 0x4700
	s_addc_u32 s15, s69, 0
	s_add_u32 s18, s68, 0x4800
	s_addc_u32 s19, s69, 0
	s_add_u32 s20, s68, 0x4900
	s_addc_u32 s21, s69, 0
	s_add_u32 s22, s68, 0x4a00
	s_addc_u32 s23, s69, 0
	s_add_u32 s24, s68, 0x4b00
	s_addc_u32 s25, s69, 0
	s_waitcnt lgkmcnt(0)
	s_mul_i32 s0, s4, s89
	s_add_u32 s4, s68, 0x4c00
	s_mul_i32 s0, s0, s5
	s_addc_u32 s5, s69, 0
	s_add_u32 s26, s68, 0x4d00
	s_addc_u32 s27, s69, 0
	s_add_u32 s28, s68, 0x4e00
	s_addc_u32 s29, s69, 0
	s_add_u32 s30, s68, 0x4f00
	s_addc_u32 s31, s69, 0
	s_add_u32 s34, s68, 0x5000
	s_addc_u32 s35, s69, 0
	s_add_u32 s36, s68, 0x5100
	s_addc_u32 s37, s69, 0
	s_add_u32 s40, s68, 0x5200
	s_addc_u32 s41, s69, 0
	s_add_u32 s42, s68, 0x5300
	s_addc_u32 s43, s69, 0
	s_mov_b32 s39, 1
	v_mov_b32_e32 v17, 0
	s_branch .LBB0_486

; __device__ __forceinline__ int tid_fresh() { int t = threadIdx.x; asm volatile("" : "+v"(t)); return t; }
; #define PG8_STAGE(bufoff, gbase, voff) do { _Pragma("unroll") for (int _i = 0; _i < 2; ++_i) \
;         __builtin_amdgcn_global_load_lds((const unsigned*)((const char*)(gbase) + (voff)[_i]), (LAS unsigned*)(lds + (bufoff) + ldsw + _i * 8192), 16, 0, 0); } while (0)
; #define PG8_WAIT_V(n) asm volatile("s_waitcnt vmcnt(" #n ")" ::: "memory")
; #define PG8_BAR __builtin_amdgcn_s_barrier()
; template <class Epi, class Sched, bool ABLK = false, bool ALIGN_EPI = true, bool SP2 = true, bool BBLK = true>
; __device__ __forceinline__ void gemm_phase(LAS unsigned char* lds, const Gemm g, const Sched& S, const Epi& E) {
;     const int tid = tid_fresh(), wid = __builtin_amdgcn_readfirstlane(tid >> 6), lane = tid & 63, wr = wid >> 2, wc = wid & 3, fr = lane & 15, fq = lane >> 4;
;     unsigned voffA[2], voffB[2];
; #pragma unroll
;     for (int i = 0; i < 2; ++i) { int R, C; stage_rc(tid * 16 + i * 8192, R, C); const int r32 = Epi::PERM ? perm32(R & 31) : (R & 31);
;         const int Rb = Epi::ADJ ? 64 * (R >> 5) + r32 : (R & ~31) + r32;
;         voffA[i] = (unsigned)(R * (ABLK ? 64 : g.lda) + C) * 2u; voffB[i] = BBLK ? (unsigned)(R * 64 + C) * 2u : (unsigned)(Rb * g.ldb + C) * 2u; }
;     ...
;     const char* uA = a_unit(cur); int tbA = cur.k0 / BK;
;     const char* cA = a_tile(uA, tbA); const char* cB = (const char*)g.Bt + (size_t)cur.pn * tstepB + b_k0(cur.k0);
;     S.a_ready(cur);
;     if constexpr (SP2) {
;         PG8_STAGE(PG8_SB(0, 0), cB, voffB); PG8_STAGE(PG8_SB(0, 1), cB + hstepB, voffB); PG8_STAGE(PG8_SA(0, 0), cA, voffA); PG8_STAGE(PG8_SA(0, 1), cA + hstepA, voffA);
;         if (wr == 1) PG8_BAR;
;         PG8_WAIT_V(2); PG8_BAR;
;         PG8_STAGE(PG8_SB(1, 0), cB + kstepB, voffB); PG8_STAGE(PG8_SA(1, 0), a_tile(uA, tbA + 1), voffA); PG8_STAGE(PG8_SB(1, 1), cB + hstepB + kstepB, voffB);
;         PG8_WAIT_V(6); PG8_BAR;
;     } else {
;         PG8_STAGE(PG8_SB(0, 0), cB, voffB); PG8_STAGE(PG8_SA(0, 0), cA, voffA); PG8_STAGE(PG8_SB(0, 1), cB + hstepB, voffB); PG8_STAGE(PG8_SA(0, 1), cA + hstepA, voffA);
;         if (wr == 1) PG8_BAR;
.LBB0_534:
	s_or_b64 exec, exec, s[2:3]
	v_mov_b32_e32 v6, v0
	s_waitcnt lgkmcnt(0)
	s_barrier
	s_add_u32 s39, s68, 0xe900000
	v_bfe_i32 v3, v6, 27, 1
	v_lshlrev_b32_e32 v1, 4, v6
	v_lshrrev_b32_e32 v3, 22, v3
	v_add_u32_e32 v3, v1, v3
	v_and_b32_e32 v3, 0xfffffc00, v3
	v_sub_u32_e32 v3, v1, v3
	v_lshrrev_b32_e32 v4, 4, v3
	v_bitop3_b32 v4, v4, v3, 32 bitop3:0x6c
	v_ashrrev_i32_e32 v3, 31, v3
	v_lshrrev_b32_e32 v3, 26, v3
	v_ashrrev_i32_e32 v2, 31, v6
	v_add_u32_e32 v3, v4, v3
	v_lshrrev_b32_e32 v2, 26, v2
	v_ashrrev_i32_e32 v3, 6, v3
	v_add_u32_e32 v2, v6, v2
	v_mul_i32_i24_e32 v8, 64, v3
	v_ashrrev_i32_e32 v2, 6, v2
	v_sub_u32_e32 v4, v4, v8
	v_mov_b32_e32 v8, 1
	v_lshlrev_b32_e32 v5, 3, v2
	v_lshlrev_b32_e32 v7, 5, v2
	v_ashrrev_i16_sdwa v4, v8, sext(v4) dst_sel:DWORD dst_unused:UNUSED_PAD src0_sel:DWORD src1_sel:BYTE_0
	v_and_b32_e32 v5, 0x1fffff0, v5
	v_and_b32_e32 v7, 32, v7
	v_bfe_i32 v4, v4, 0, 16
	v_add_u32_e32 v7, v7, v4
	v_add_lshl_u32 v5, v3, v5, 7
	v_add_u32_e32 v1, 0x2000, v1
	v_lshl_add_u32 v130, v7, 1, v5
	v_ashrrev_i32_e32 v5, 31, v1
	v_lshrrev_b32_e32 v5, 22, v5
	v_add_u32_e32 v5, v1, v5
	v_ashrrev_i32_e32 v5, 10, v5
	v_mul_i32_i24_e32 v7, 0x400, v5
	v_sub_u32_e32 v1, v1, v7
	v_lshrrev_b32_e32 v7, 4, v1
	v_bitop3_b32 v1, v7, v1, 32 bitop3:0x6c
	v_lshlrev_b32_e32 v7, 3, v5
	s_addc_u32 s50, s69, 0
	v_and_b32_e32 v9, 0x1fffff0, v7
	v_ashrrev_i32_e32 v7, 31, v1
	s_lshl_b32 s2, s91, 2
	s_ashr_i32 s3, s90, 6
	v_readfirstlane_b32 s0, v6
	v_lshrrev_b32_e32 v7, 26, v7
	s_add_i32 s82, s2, s3
	s_ashr_i32 s5, s0, 6
	v_add_u32_e32 v10, v1, v7
	s_bfe_u32 s78, s90, 0x30003
	s_ashr_i32 s83, s82, 31
	v_ashrrev_i32_e32 v7, 6, v10
	v_and_b32_e32 v10, 0xc0, v10
	s_ashr_i32 s4, s0, 8
	s_lshl_b32 s51, s5, 10
	s_lshl_b64 s[6:7], s[82:83], 22
	s_lshl_b32 s2, s78, 22
	v_sub_u32_e32 v1, v1, v10
	s_add_u32 s40, s39, s2
	v_lshlrev_b32_e32 v11, 5, v5
	v_ashrrev_i16_sdwa v1, v8, sext(v1) dst_sel:DWORD dst_unused:UNUSED_PAD src0_sel:DWORD src1_sel:BYTE_0
	s_addc_u32 s41, s50, 0
	s_add_i32 s52, s51, 0
	v_and_b32_e32 v11, 32, v11
	v_bfe_i32 v8, v1, 0, 16
	s_add_i32 m0, s52, 0x10000
	v_add_u32_e32 v1, v11, v8
	v_add_lshl_u32 v9, v7, v9, 7
	global_load_lds_dwordx4 v130, s[40:41]
	s_add_i32 m0, s52, 0x12000
	v_lshl_add_u32 v132, v1, 1, v9
	v_writelane_b32 v252, s2, 16
	s_add_u32 s2, s40, 0x4000
	global_load_lds_dwordx4 v132, s[40:41]
	s_addc_u32 s3, s41, 0
	s_add_i32 m0, s52, 0x14000
	v_mov_b32_e32 v131, 0
	global_load_lds_dwordx4 v130, s[2:3]
	s_add_i32 m0, s52, 0x16000
	s_add_u32 s42, s1, s6
	v_writelane_b32 v252, s6, 17
	s_addc_u32 s43, s33, s7
	s_add_i32 s53, s52, 0x2000
	global_load_lds_dwordx4 v132, s[2:3]
	s_mov_b32 m0, s52
	s_add_u32 s2, s42, 0x4000
	global_load_lds_dwordx4 v130, s[42:43]
	s_mov_b32 m0, s53
	s_addc_u32 s3, s43, 0
	s_add_i32 s54, s52, 0x4000
	global_load_lds_dwordx4 v132, s[42:43]
	s_mov_b32 m0, s54
	s_add_i32 s55, s52, 0x6000
	global_load_lds_dwordx4 v130, s[2:3]
	s_mov_b32 m0, s55
	s_cmp_eq_u32 s4, 1
	global_load_lds_dwordx4 v132, s[2:3]
	s_mov_b32 s58, 0
	s_cselect_b64 s[2:3], -1, 0
	s_cmp_lg_u32 s4, 1
	v_mov_b32_e32 v133, v131
	v_writelane_b32 v252, s7, 18
	s_cbranch_scc1 .LBB0_536
	s_setprio 1
	s_barrier

; #define PG8_WAIT_V(n) asm volatile("s_waitcnt vmcnt(" #n ")" ::: "memory")
; #define PG8_BAR __builtin_amdgcn_s_barrier()
; __device__ __forceinline__ unsigned xb_add(unsigned* p, unsigned v) { return __hip_atomic_fetch_add(p, v, __ATOMIC_RELAXED, __HIP_MEMORY_SCOPE_AGENT); }
; template <class Epi, class Sched, bool ABLK = false, bool ALIGN_EPI = true, bool SP2 = true, bool BBLK = true>
; __device__ __forceinline__ void gemm_phase(LAS unsigned char* lds, const Gemm g, const Sched& S, const Epi& E) {
;     ...
;     PG8_WAIT_V(0);
;     if constexpr (!ALIGN_EPI) { if (wr == 0) PG8_BAR; }
;     PG8_BAR;
; __device__ __forceinline__ void xcd_barrier(const XcdBarrier& b) {
;     asm volatile("s_waitcnt vmcnt(0)" ::: "memory");
;     __syncthreads();
;     if (threadIdx.x == 0) {
;         unsigned* bar = b.bar;
;         __builtin_amdgcn_s_waitcnt(0);
;         unsigned nloc = b.st[0], nx = b.st[1];
;         if (nloc == 0u) { xcd_barrier_complete(bar, b.x, nloc, nx); b.st[0] = nloc; b.st[1] = nx; }
;         const unsigned old = xb_add(&bar[XB_XSUB(b.x)], 1u);
;         const unsigned gen = old / nloc;
.LBB0_546:
	s_waitcnt vmcnt(0)
	s_barrier
	s_waitcnt vmcnt(0)
	s_waitcnt vmcnt(0)
	s_setprio 0
	s_barrier
	s_and_saveexec_b64 s[2:3], s[92:93]
	s_cbranch_execz .LBB0_598
	s_add_i32 s1, 0, 0x20000
	v_mov_b32_e32 v1, s1
	s_waitcnt vmcnt(0) expcnt(0) lgkmcnt(0)
	ds_read_b32 v3, v1
	s_add_i32 s1, 0, 0x20004
	v_mov_b32_e32 v1, s1
	ds_read_b32 v1, v1
	s_waitcnt lgkmcnt(1)
	v_cmp_ne_u32_e32 vcc, 0, v3
	s_cbranch_vccnz .LBB0_562
	v_readlane_b32 s6, v252, 7
	v_readlane_b32 s7, v252, 8
	s_load_dwordx2 s[4:5], s[6:7], 0x4
	s_add_u32 s6, s68, 0x4200
	s_addc_u32 s7, s69, 0
	s_add_u32 s8, s68, 0x4400
	s_addc_u32 s9, s69, 0
	s_add_u32 s10, s68, 0x4500
	s_addc_u32 s11, s69, 0
	s_add_u32 s12, s68, 0x4600
	s_addc_u32 s13, s69, 0
	s_add_u32 s14, s68, 0x4700
	s_addc_u32 s15, s69, 0
	s_add_u32 s16, s68, 0x4800
	s_addc_u32 s17, s69, 0
	s_add_u32 s18, s68, 0x4900
	s_addc_u32 s19, s69, 0
	s_add_u32 s20, s68, 0x4a00
	s_addc_u32 s21, s69, 0
	s_add_u32 s22, s68, 0x4b00
	s_addc_u32 s23, s69, 0
	s_waitcnt lgkmcnt(0)
	s_mul_i32 s1, s4, s89
	s_add_u32 s4, s68, 0x4c00
	s_mul_i32 s1, s1, s5
	s_addc_u32 s5, s69, 0
	s_add_u32 s24, s68, 0x4d00
	s_addc_u32 s25, s69, 0
	s_add_u32 s26, s68, 0x4e00
	s_addc_u32 s27, s69, 0
	s_add_u32 s28, s68, 0x4f00
	s_addc_u32 s29, s69, 0
	s_add_u32 s30, s68, 0x5000
	s_addc_u32 s31, s69, 0
	s_add_u32 s34, s68, 0x5100
	s_addc_u32 s35, s69, 0
	s_add_u32 s36, s68, 0x5200
	s_addc_u32 s37, s69, 0
	s_add_u32 s40, s68, 0x5300
	s_addc_u32 s41, s69, 0
	s_mov_b32 s33, 1
	v_mov_b32_e32 v17, 0
	s_branch .LBB0_550

; __device__ __forceinline__ int tid_fresh() { int t = threadIdx.x; asm volatile("" : "+v"(t)); return t; }
; #define PG8_STAGE(bufoff, gbase, voff) do { _Pragma("unroll") for (int _i = 0; _i < 2; ++_i) \
;         __builtin_amdgcn_global_load_lds((const unsigned*)((const char*)(gbase) + (voff)[_i]), (LAS unsigned*)(lds + (bufoff) + ldsw + _i * 8192), 16, 0, 0); } while (0)
; #define PG8_WAIT_V(n) asm volatile("s_waitcnt vmcnt(" #n ")" ::: "memory")
; #define PG8_BAR __builtin_amdgcn_s_barrier()
; template <class Epi, class Sched, bool ABLK = false, bool ALIGN_EPI = true, bool SP2 = true, bool BBLK = true>
; __device__ __forceinline__ void gemm_phase(LAS unsigned char* lds, const Gemm g, const Sched& S, const Epi& E) {
;     const int tid = tid_fresh(), wid = __builtin_amdgcn_readfirstlane(tid >> 6), lane = tid & 63, wr = wid >> 2, wc = wid & 3, fr = lane & 15, fq = lane >> 4;
;     unsigned voffA[2], voffB[2];
; #pragma unroll
;     for (int i = 0; i < 2; ++i) { int R, C; stage_rc(tid * 16 + i * 8192, R, C); const int r32 = Epi::PERM ? perm32(R & 31) : (R & 31);
;         const int Rb = Epi::ADJ ? 64 * (R >> 5) + r32 : (R & ~31) + r32;
;         voffA[i] = (unsigned)(R * (ABLK ? 64 : g.lda) + C) * 2u; voffB[i] = BBLK ? (unsigned)(R * 64 + C) * 2u : (unsigned)(Rb * g.ldb + C) * 2u; }
;     ...
;     const char* uA = a_unit(cur); int tbA = cur.k0 / BK;
;     const char* cA = a_tile(uA, tbA); const char* cB = (const char*)g.Bt + (size_t)cur.pn * tstepB + b_k0(cur.k0);
;     S.a_ready(cur);
;     if constexpr (SP2) {
;         PG8_STAGE(PG8_SB(0, 0), cB, voffB); PG8_STAGE(PG8_SB(0, 1), cB + hstepB, voffB); PG8_STAGE(PG8_SA(0, 0), cA, voffA); PG8_STAGE(PG8_SA(0, 1), cA + hstepA, voffA);
;         if (wr == 1) PG8_BAR;
;         PG8_WAIT_V(2); PG8_BAR;
;         PG8_STAGE(PG8_SB(1, 0), cB + kstepB, voffB); PG8_STAGE(PG8_SA(1, 0), a_tile(uA, tbA + 1), voffA); PG8_STAGE(PG8_SB(1, 1), cB + hstepB + kstepB, voffB);
;         PG8_WAIT_V(6); PG8_BAR;
;     } else {
;         PG8_STAGE(PG8_SB(0, 0), cB, voffB); PG8_STAGE(PG8_SA(0, 0), cA, voffA); PG8_STAGE(PG8_SB(0, 1), cB + hstepB, voffB); PG8_STAGE(PG8_SA(0, 1), cA + hstepA, voffA);
;         if (wr == 1) PG8_BAR;
.LBB0_659:
	s_load_dwordx4 s[12:15], s[86:87], 0xf0
	s_waitcnt lgkmcnt(0)
	s_add_u32 s59, s14, 0x1b900000
	s_addc_u32 s62, s15, 0
	s_add_u32 s1, s14, 0x23100000
	s_addc_u32 s33, s15, 0
	s_andn2_b64 vcc, exec, s[2:3]
	s_cbranch_vccnz .LBB0_712
	v_ashrrev_i32_e32 v3, 31, v1
	v_lshrrev_b32_e32 v3, 26, v3
	v_add_u32_e32 v3, v1, v3
	v_ashrrev_i32_e32 v6, 6, v3
	v_bfe_i32 v3, v1, 27, 1
	v_lshlrev_b32_e32 v2, 4, v1
	v_lshrrev_b32_e32 v3, 22, v3
	v_add_u32_e32 v3, v2, v3
	v_and_b32_e32 v3, 0xfffffc00, v3
	v_sub_u32_e32 v3, v2, v3
	v_lshrrev_b32_e32 v4, 4, v3
	v_bitop3_b32 v4, v4, v3, 32 bitop3:0x6c
	v_ashrrev_i32_e32 v3, 31, v3
	v_lshrrev_b32_e32 v3, 26, v3
	v_add_u32_e32 v3, v4, v3
	v_ashrrev_i32_e32 v7, 6, v3
	v_lshlrev_b32_e32 v5, 3, v6
	v_mul_i32_i24_e32 v8, 64, v7
	v_and_b32_e32 v5, -16, v5
	v_sub_u32_e32 v4, v4, v8
	v_mov_b32_e32 v11, 1
	v_add_u32_e32 v3, v7, v5
	v_lshlrev_b32_e32 v5, 5, v6
	v_ashrrev_i16_sdwa v4, v11, sext(v4) dst_sel:DWORD dst_unused:UNUSED_PAD src0_sel:DWORD src1_sel:BYTE_0
	v_and_b32_e32 v5, 32, v5
	v_bfe_i32 v8, v4, 0, 16
	v_add_u32_e32 v4, v5, v8
	v_lshlrev_b32_e32 v5, 12, v3
	v_lshl_add_u32 v130, v4, 1, v5
	s_movk_i32 s3, 0xf080
	v_add_u32_e32 v2, 0x2000, v2
	v_mad_u64_u32 v[132:133], s[6:7], v3, s3, v[130:131]
	v_ashrrev_i32_e32 v3, 31, v2
	v_lshrrev_b32_e32 v3, 22, v3
	v_add_u32_e32 v3, v2, v3
	v_ashrrev_i32_e32 v9, 10, v3
	v_mul_i32_i24_e32 v3, 0x400, v9
	v_sub_u32_e32 v2, v2, v3
	v_lshrrev_b32_e32 v3, 4, v2
	v_bitop3_b32 v2, v3, v2, 32 bitop3:0x6c
	v_ashrrev_i32_e32 v4, 31, v2
	v_lshrrev_b32_e32 v4, 26, v4
	v_add_u32_e32 v4, v2, v4
	s_load_dwordx4 s[12:15], s[86:87], 0xf0
	v_ashrrev_i32_e32 v10, 6, v4
	v_and_b32_e32 v4, 0xc0, v4
	v_lshlrev_b32_e32 v3, 3, v9
	v_sub_u32_e32 v2, v2, v4
	v_and_b32_e32 v3, -16, v3
	v_lshlrev_b32_e32 v5, 5, v9
	v_ashrrev_i16_sdwa v2, v11, sext(v2) dst_sel:DWORD dst_unused:UNUSED_PAD src0_sel:DWORD src1_sel:BYTE_0
	v_add_u32_e32 v3, v10, v3
	v_and_b32_e32 v5, 32, v5
	v_bfe_i32 v11, v2, 0, 16
	v_add_u32_e32 v2, v5, v11
	v_lshlrev_b32_e32 v4, 12, v3
	s_waitcnt lgkmcnt(0)
	s_add_u32 s39, s14, 0x2100000
	v_lshl_add_u32 v134, v2, 1, v4
	s_addc_u32 s40, s15, 0
	s_ashr_i32 s2, s4, 6
	v_mad_u64_u32 v[136:137], s[6:7], v3, s3, v[134:135]
	s_ashr_i32 s25, s24, 31
	s_ashr_i32 s9, s8, 31
	s_ashr_i32 s5, s4, 8
	s_lshl_b32 s41, s2, 10
	s_lshl_b64 s[6:7], s[24:25], 20
	s_lshl_b64 s[10:11], s[8:9], 20
	s_add_u32 s28, s39, s10
	s_addc_u32 s29, s40, s11
	s_add_i32 s25, s41, 0
	s_add_i32 m0, s25, 0x10000
	v_mov_b32_e32 v139, 0
	global_load_lds_dwordx4 v132, s[28:29]
	s_add_i32 m0, s25, 0x12000
	s_add_u32 s10, s28, 0x4000
	global_load_lds_dwordx4 v136, s[28:29]
	s_addc_u32 s11, s29, 0
	s_add_i32 m0, s25, 0x14000
	v_mov_b32_e32 v131, v139
	global_load_lds_dwordx4 v132, s[10:11]
	s_add_i32 m0, s25, 0x16000
	s_add_u32 s26, s59, s6
	s_addc_u32 s27, s62, s7
	s_add_i32 s42, s25, 0x2000
	global_load_lds_dwordx4 v136, s[10:11]
	s_mov_b32 m0, s25
	s_add_u32 s6, s26, 0x80000
	global_load_lds_dwordx4 v130, s[26:27]
	s_mov_b32 m0, s42
	s_addc_u32 s7, s27, 0
	s_add_i32 s43, s25, 0x4000
	global_load_lds_dwordx4 v134, s[26:27]
	s_mov_b32 m0, s43
	s_add_i32 s46, s25, 0x6000
	global_load_lds_dwordx4 v130, s[6:7]
	s_mov_b32 m0, s46
	v_mov_b32_e32 v135, v139
	global_load_lds_dwordx4 v134, s[6:7]
	s_cmp_eq_u32 s5, 1
	s_mov_b32 s3, 0
	v_mov_b32_e32 v133, v139
	v_mov_b32_e32 v137, v139
	v_lshl_add_u64 v[2:3], s[26:27], 0, v[130:131]
	s_cselect_b64 s[10:11], -1, 0
	s_cmp_lg_u32 s5, 1
	v_lshl_add_u64 v[4:5], s[26:27], 0, v[134:135]
	s_cbranch_scc1 .LBB0_662
	s_setprio 1
	s_barrier

; #define PG8_WAIT_V(n) asm volatile("s_waitcnt vmcnt(" #n ")" ::: "memory")
; #define PG8_BAR __builtin_amdgcn_s_barrier()
; __device__ __forceinline__ unsigned xb_add(unsigned* p, unsigned v) { return __hip_atomic_fetch_add(p, v, __ATOMIC_RELAXED, __HIP_MEMORY_SCOPE_AGENT); }
; template <class Epi, class Sched, bool ABLK = false, bool ALIGN_EPI = true, bool SP2 = true, bool BBLK = true>
; __device__ __forceinline__ void gemm_phase(LAS unsigned char* lds, const Gemm g, const Sched& S, const Epi& E) {
;     ...
;     PG8_WAIT_V(0);
;     if constexpr (!ALIGN_EPI) { if (wr == 0) PG8_BAR; }
;     PG8_BAR;
; __device__ __forceinline__ void xcd_barrier(const XcdBarrier& b) {
;     asm volatile("s_waitcnt vmcnt(0)" ::: "memory");
;     __syncthreads();
;     if (threadIdx.x == 0) {
;         unsigned* bar = b.bar;
;         __builtin_amdgcn_s_waitcnt(0);
;         unsigned nloc = b.st[0], nx = b.st[1];
;         if (nloc == 0u) { xcd_barrier_complete(bar, b.x, nloc, nx); b.st[0] = nloc; b.st[1] = nx; }
;         const unsigned old = xb_add(&bar[XB_XSUB(b.x)], 1u);
;         const unsigned gen = old / nloc;
.LBB0_712:
	s_waitcnt vmcnt(0)
	s_waitcnt vmcnt(0)
	s_setprio 0
	s_barrier
	s_and_saveexec_b64 s[2:3], s[92:93]
	s_cbranch_execz .LBB0_764
	s_add_i32 s4, 0, 0x20000
	v_mov_b32_e32 v1, s4
	s_waitcnt vmcnt(0) expcnt(0) lgkmcnt(0)
	ds_read_b32 v3, v1
	s_add_i32 s4, 0, 0x20004
	v_mov_b32_e32 v1, s4
	ds_read_b32 v1, v1
	s_waitcnt lgkmcnt(1)
	v_cmp_ne_u32_e32 vcc, 0, v3
	s_cbranch_vccnz .LBB0_728
	v_readlane_b32 s6, v252, 7
	v_readlane_b32 s7, v252, 8
	s_load_dwordx2 s[4:5], s[6:7], 0x4
	s_add_u32 s6, s68, 0x4200
	s_addc_u32 s7, s69, 0
	s_add_u32 s8, s68, 0x4400
	s_addc_u32 s9, s69, 0
	s_add_u32 s10, s68, 0x4500
	s_addc_u32 s11, s69, 0
	s_add_u32 s12, s68, 0x4600
	s_addc_u32 s13, s69, 0
	s_add_u32 s14, s68, 0x4700
	s_addc_u32 s15, s69, 0
	s_add_u32 s16, s68, 0x4800
	s_addc_u32 s17, s69, 0
	s_add_u32 s18, s68, 0x4900
	s_addc_u32 s19, s69, 0
	s_add_u32 s20, s68, 0x4a00
	s_addc_u32 s21, s69, 0
	s_add_u32 s22, s68, 0x4b00
	s_addc_u32 s23, s69, 0
	s_waitcnt lgkmcnt(0)
	s_mul_i32 s39, s4, s89
	s_add_u32 s4, s68, 0x4c00
	s_mul_i32 s39, s39, s5
	s_addc_u32 s5, s69, 0
	s_add_u32 s24, s68, 0x4d00
	s_addc_u32 s25, s69, 0
	s_add_u32 s26, s68, 0x4e00
	s_addc_u32 s27, s69, 0
	s_add_u32 s28, s68, 0x4f00
	s_addc_u32 s29, s69, 0
	s_add_u32 s30, s68, 0x5000
	s_addc_u32 s31, s69, 0
	s_add_u32 s34, s68, 0x5100
	s_addc_u32 s35, s69, 0
	s_add_u32 s36, s68, 0x5200
	s_addc_u32 s37, s69, 0
	s_add_u32 s40, s68, 0x5300
	s_addc_u32 s41, s69, 0
	s_mov_b32 s50, 1
	v_mov_b32_e32 v17, 0
	s_branch .LBB0_716

; __device__ __forceinline__ int tid_fresh() { int t = threadIdx.x; asm volatile("" : "+v"(t)); return t; }
; #define PG8_STAGE(bufoff, gbase, voff) do { _Pragma("unroll") for (int _i = 0; _i < 2; ++_i) \
;         __builtin_amdgcn_global_load_lds((const unsigned*)((const char*)(gbase) + (voff)[_i]), (LAS unsigned*)(lds + (bufoff) + ldsw + _i * 8192), 16, 0, 0); } while (0)
; #define PG8_WAIT_V(n) asm volatile("s_waitcnt vmcnt(" #n ")" ::: "memory")
; #define PG8_BAR __builtin_amdgcn_s_barrier()
; template <class Epi, class Sched, bool ABLK = false, bool ALIGN_EPI = true, bool SP2 = true, bool BBLK = true>
; __device__ __forceinline__ void gemm_phase(LAS unsigned char* lds, const Gemm g, const Sched& S, const Epi& E) {
;     const int tid = tid_fresh(), wid = __builtin_amdgcn_readfirstlane(tid >> 6), lane = tid & 63, wr = wid >> 2, wc = wid & 3, fr = lane & 15, fq = lane >> 4;
;     unsigned voffA[2], voffB[2];
; #pragma unroll
;     for (int i = 0; i < 2; ++i) { int R, C; stage_rc(tid * 16 + i * 8192, R, C); const int r32 = Epi::PERM ? perm32(R & 31) : (R & 31);
;         const int Rb = Epi::ADJ ? 64 * (R >> 5) + r32 : (R & ~31) + r32;
;         voffA[i] = (unsigned)(R * (ABLK ? 64 : g.lda) + C) * 2u; voffB[i] = BBLK ? (unsigned)(R * 64 + C) * 2u : (unsigned)(Rb * g.ldb + C) * 2u; }
;     ...
;     const char* uA = a_unit(cur); int tbA = cur.k0 / BK;
;     const char* cA = a_tile(uA, tbA); const char* cB = (const char*)g.Bt + (size_t)cur.pn * tstepB + b_k0(cur.k0);
;     S.a_ready(cur);
;     if constexpr (SP2) {
;         PG8_STAGE(PG8_SB(0, 0), cB, voffB); PG8_STAGE(PG8_SB(0, 1), cB + hstepB, voffB); PG8_STAGE(PG8_SA(0, 0), cA, voffA); PG8_STAGE(PG8_SA(0, 1), cA + hstepA, voffA);
;         if (wr == 1) PG8_BAR;
;         PG8_WAIT_V(2); PG8_BAR;
;         PG8_STAGE(PG8_SB(1, 0), cB + kstepB, voffB); PG8_STAGE(PG8_SA(1, 0), a_tile(uA, tbA + 1), voffA); PG8_STAGE(PG8_SB(1, 1), cB + hstepB + kstepB, voffB);
;         PG8_WAIT_V(6); PG8_BAR;
;     } else {
;         PG8_STAGE(PG8_SB(0, 0), cB, voffB); PG8_STAGE(PG8_SA(0, 0), cA, voffA); PG8_STAGE(PG8_SB(0, 1), cB + hstepB, voffB); PG8_STAGE(PG8_SA(0, 1), cA + hstepA, voffA);
;         if (wr == 1) PG8_BAR;
.LBB0_1032:
	s_or_b64 exec, exec, s[2:3]
	s_waitcnt vmcnt(7)
	v_mov_b32_e32 v8, v0
	s_waitcnt lgkmcnt(0)
	s_barrier
	v_readlane_b32 s4, v252, 19
	v_ashrrev_i32_e32 v3, 31, v8
	v_lshrrev_b32_e32 v3, 26, v3
	v_add_u32_e32 v3, v8, v3
	v_ashrrev_i32_e32 v6, 6, v3
	v_bfe_i32 v3, v8, 27, 1
	v_lshlrev_b32_e32 v2, 4, v8
	v_lshrrev_b32_e32 v3, 22, v3
	v_add_u32_e32 v3, v2, v3
	v_and_b32_e32 v3, 0xfffffc00, v3
	v_sub_u32_e32 v3, v2, v3
	v_lshrrev_b32_e32 v4, 4, v3
	v_bitop3_b32 v4, v4, v3, 32 bitop3:0x6c
	v_ashrrev_i32_e32 v3, 31, v3
	v_lshrrev_b32_e32 v3, 26, v3
	v_add_u32_e32 v3, v4, v3
	v_ashrrev_i32_e32 v7, 6, v3
	v_lshlrev_b32_e32 v5, 3, v6
	v_mul_i32_i24_e32 v9, 64, v7
	v_and_b32_e32 v5, -16, v5
	v_sub_u32_e32 v4, v4, v9
	s_waitcnt vmcnt(6)
	v_mov_b32_e32 v12, 1
	v_readlane_b32 s6, v252, 21
	v_add_u32_e32 v3, v7, v5
	v_lshlrev_b32_e32 v5, 5, v6
	v_ashrrev_i16_sdwa v4, v12, sext(v4) dst_sel:DWORD dst_unused:UNUSED_PAD src0_sel:DWORD src1_sel:BYTE_0
	v_readlane_b32 s7, v252, 22
	s_add_u32 s28, s6, 0x2d100000
	v_and_b32_e32 v5, 32, v5
	v_bfe_i32 v9, v4, 0, 16
	s_addc_u32 s29, s7, 0
	v_add_u32_e32 v4, v5, v9
	v_lshlrev_b32_e32 v5, 12, v3
	s_add_u32 s30, s6, 0x3900000
	v_lshl_add_u32 v130, v4, 1, v5
	s_movk_i32 s6, 0xf080
	v_add_u32_e32 v2, 0x2000, v2
	v_mad_u64_u32 v[132:133], s[2:3], v3, s6, v[130:131]
	v_ashrrev_i32_e32 v3, 31, v2
	v_lshrrev_b32_e32 v3, 22, v3
	v_add_u32_e32 v3, v2, v3
	v_ashrrev_i32_e32 v10, 10, v3
	v_mul_i32_i24_e32 v3, 0x400, v10
	v_sub_u32_e32 v2, v2, v3
	v_lshrrev_b32_e32 v3, 4, v2
	v_bitop3_b32 v2, v3, v2, 32 bitop3:0x6c
	v_ashrrev_i32_e32 v4, 31, v2
	v_lshrrev_b32_e32 v4, 26, v4
	v_add_u32_e32 v4, v2, v4
	v_ashrrev_i32_e32 v11, 6, v4
	v_and_b32_e32 v4, 0xc0, v4
	v_lshlrev_b32_e32 v3, 3, v10
	v_sub_u32_e32 v2, v2, v4
	v_and_b32_e32 v3, -16, v3
	v_lshlrev_b32_e32 v5, 5, v10
	v_ashrrev_i16_sdwa v2, v12, sext(v2) dst_sel:DWORD dst_unused:UNUSED_PAD src0_sel:DWORD src1_sel:BYTE_0
	v_add_u32_e32 v3, v11, v3
	v_and_b32_e32 v5, 32, v5
	v_bfe_i32 v12, v2, 0, 16
	v_readlane_b32 s5, v252, 20
	v_readfirstlane_b32 s4, v8
	v_add_u32_e32 v2, v5, v12
	v_lshlrev_b32_e32 v4, 12, v3
	s_addc_u32 s31, s7, 0
	s_ashr_i32 s5, s4, 6
	v_lshl_add_u32 v134, v2, 1, v4
	v_mad_u64_u32 v[136:137], s[2:3], v3, s6, v[134:135]
	s_ashr_i32 s6, s4, 8
	s_lshl_b32 s34, s5, 10
	s_lshl_b64 s[8:9], s[82:83], 20
	s_lshl_b32 s97, s78, 20
	s_add_u32 s20, s30, s97
	s_addc_u32 s21, s31, 0
	s_add_i32 s35, s34, 0
	s_add_i32 m0, s35, 0x10000
	v_mov_b32_e32 v133, 0
	global_load_lds_dwordx4 v132, s[20:21]
	s_add_i32 m0, s35, 0x12000
	s_add_u32 s2, s20, 0x4000
	global_load_lds_dwordx4 v136, s[20:21]
	s_addc_u32 s3, s21, 0
	s_add_i32 m0, s35, 0x14000
	v_mov_b32_e32 v131, v133
	global_load_lds_dwordx4 v132, s[2:3]
	s_add_i32 m0, s35, 0x16000
	s_add_u32 s22, s28, s8
	v_writelane_b32 v252, s8, 24
	s_addc_u32 s23, s29, s9
	s_add_i32 s36, s35, 0x2000
	global_load_lds_dwordx4 v136, s[2:3]
	s_mov_b32 m0, s35
	s_add_u32 s2, s22, 0x80000
	global_load_lds_dwordx4 v130, s[22:23]
	s_mov_b32 m0, s36
	s_addc_u32 s3, s23, 0
	s_add_i32 s37, s35, 0x4000
	global_load_lds_dwordx4 v134, s[22:23]
	s_mov_b32 m0, s37
	s_add_i32 s40, s35, 0x6000
	global_load_lds_dwordx4 v130, s[2:3]
	s_mov_b32 m0, s40
	v_mov_b32_e32 v135, v133
	global_load_lds_dwordx4 v134, s[2:3]
	s_cmp_eq_u32 s6, 1
	s_mov_b32 s46, 32
	s_mov_b32 s43, 0
	v_mov_b32_e32 v137, v133
	v_lshl_add_u64 v[2:3], s[22:23], 0, v[130:131]
	s_cselect_b64 s[2:3], -1, 0
	s_cmp_lg_u32 s6, 1
	v_lshl_add_u64 v[4:5], s[22:23], 0, v[134:135]
	v_writelane_b32 v252, s9, 25
	s_cbranch_scc1 .LBB0_1034
	s_setprio 1
	s_barrier

; #define PG8_WAIT_V(n) asm volatile("s_waitcnt vmcnt(" #n ")" ::: "memory")
; #define PG8_BAR __builtin_amdgcn_s_barrier()
; __device__ __forceinline__ unsigned xb_add(unsigned* p, unsigned v) { return __hip_atomic_fetch_add(p, v, __ATOMIC_RELAXED, __HIP_MEMORY_SCOPE_AGENT); }
; template <class Epi, class Sched, bool ABLK = false, bool ALIGN_EPI = true, bool SP2 = true, bool BBLK = true>
; __device__ __forceinline__ void gemm_phase(LAS unsigned char* lds, const Gemm g, const Sched& S, const Epi& E) {
;     ...
;     PG8_WAIT_V(0);
;     if constexpr (!ALIGN_EPI) { if (wr == 0) PG8_BAR; }
;     PG8_BAR;
; __device__ __forceinline__ void xcd_barrier(const XcdBarrier& b) {
;     asm volatile("s_waitcnt vmcnt(0)" ::: "memory");
;     __syncthreads();
;     if (threadIdx.x == 0) {
;         unsigned* bar = b.bar;
;         __builtin_amdgcn_s_waitcnt(0);
;         unsigned nloc = b.st[0], nx = b.st[1];
;         if (nloc == 0u) { xcd_barrier_complete(bar, b.x, nloc, nx); b.st[0] = nloc; b.st[1] = nx; }
;         const unsigned old = xb_add(&bar[XB_XSUB(b.x)], 1u);
;         const unsigned gen = old / nloc;
.LBB0_1044:
	s_waitcnt vmcnt(0)
	s_barrier
	s_waitcnt vmcnt(0)
	s_waitcnt vmcnt(0)
	s_setprio 0
	s_barrier
	s_and_saveexec_b64 s[2:3], s[92:93]
	s_cbranch_execz .LBB0_1096
	s_add_i32 s4, 0, 0x20000
	v_mov_b32_e32 v2, s4
	s_waitcnt vmcnt(0) expcnt(0) lgkmcnt(0)
	ds_read_b32 v4, v2
	s_add_i32 s4, 0, 0x20004
	v_mov_b32_e32 v2, s4
	ds_read_b32 v2, v2
	s_waitcnt lgkmcnt(1)
	v_cmp_ne_u32_e32 vcc, 0, v4
	s_cbranch_vccnz .LBB0_1060
	v_readlane_b32 s6, v252, 7
	v_readlane_b32 s7, v252, 8
	s_load_dwordx2 s[4:5], s[6:7], 0x4
	s_add_u32 s6, s68, 0x4200
	s_addc_u32 s7, s69, 0
	s_add_u32 s8, s68, 0x4400
	s_addc_u32 s9, s69, 0
	s_add_u32 s10, s68, 0x4500
	s_addc_u32 s11, s69, 0
	s_add_u32 s14, s68, 0x4600
	s_addc_u32 s15, s69, 0
	s_add_u32 s16, s68, 0x4700
	s_addc_u32 s17, s69, 0
	s_add_u32 s18, s68, 0x4800
	s_addc_u32 s19, s69, 0
	s_add_u32 s20, s68, 0x4900
	s_addc_u32 s21, s69, 0
	s_add_u32 s22, s68, 0x4a00
	s_addc_u32 s23, s69, 0
	s_add_u32 s24, s68, 0x4b00
	s_addc_u32 s25, s69, 0
	s_waitcnt lgkmcnt(0)
	s_mul_i32 s55, s4, s89
	s_add_u32 s4, s68, 0x4c00
	s_mul_i32 s55, s55, s5
	s_addc_u32 s5, s69, 0
	s_add_u32 s26, s68, 0x4d00
	s_addc_u32 s27, s69, 0
	s_add_u32 s28, s68, 0x4e00
	s_addc_u32 s29, s69, 0
	s_add_u32 s30, s68, 0x4f00
	s_addc_u32 s31, s69, 0
	s_add_u32 s34, s68, 0x5000
	s_addc_u32 s35, s69, 0
	s_add_u32 s36, s68, 0x5100
	s_addc_u32 s37, s69, 0
	s_add_u32 s40, s68, 0x5200
	s_addc_u32 s41, s69, 0
	s_add_u32 s42, s68, 0x5300
	s_addc_u32 s43, s69, 0
	s_mov_b32 s56, 1
	v_mov_b32_e32 v18, 0
	s_branch .LBB0_1048

; __device__ __forceinline__ int tid_fresh() { int t = threadIdx.x; asm volatile("" : "+v"(t)); return t; }
; #define PG8_STAGE(bufoff, gbase, voff) do { _Pragma("unroll") for (int _i = 0; _i < 2; ++_i) \
;         __builtin_amdgcn_global_load_lds((const unsigned*)((const char*)(gbase) + (voff)[_i]), (LAS unsigned*)(lds + (bufoff) + ldsw + _i * 8192), 16, 0, 0); } while (0)
; #define PG8_WAIT_V(n) asm volatile("s_waitcnt vmcnt(" #n ")" ::: "memory")
; #define PG8_BAR __builtin_amdgcn_s_barrier()
; template <class Epi, class Sched, bool ABLK = false, bool ALIGN_EPI = true, bool SP2 = true, bool BBLK = true>
; __device__ __forceinline__ void gemm_phase(LAS unsigned char* lds, const Gemm g, const Sched& S, const Epi& E) {
;     const int tid = tid_fresh(), wid = __builtin_amdgcn_readfirstlane(tid >> 6), lane = tid & 63, wr = wid >> 2, wc = wid & 3, fr = lane & 15, fq = lane >> 4;
;     unsigned voffA[2], voffB[2];
; #pragma unroll
;     for (int i = 0; i < 2; ++i) { int R, C; stage_rc(tid * 16 + i * 8192, R, C); const int r32 = Epi::PERM ? perm32(R & 31) : (R & 31);
;         const int Rb = Epi::ADJ ? 64 * (R >> 5) + r32 : (R & ~31) + r32;
;         voffA[i] = (unsigned)(R * (ABLK ? 64 : g.lda) + C) * 2u; voffB[i] = BBLK ? (unsigned)(R * 64 + C) * 2u : (unsigned)(Rb * g.ldb + C) * 2u; }
;     ...
;     const char* uA = a_unit(cur); int tbA = cur.k0 / BK;
;     const char* cA = a_tile(uA, tbA); const char* cB = (const char*)g.Bt + (size_t)cur.pn * tstepB + b_k0(cur.k0);
;     S.a_ready(cur);
;     if constexpr (SP2) {
;         PG8_STAGE(PG8_SB(0, 0), cB, voffB); PG8_STAGE(PG8_SB(0, 1), cB + hstepB, voffB); PG8_STAGE(PG8_SA(0, 0), cA, voffA); PG8_STAGE(PG8_SA(0, 1), cA + hstepA, voffA);
;         if (wr == 1) PG8_BAR;
;         PG8_WAIT_V(2); PG8_BAR;
;         PG8_STAGE(PG8_SB(1, 0), cB + kstepB, voffB); PG8_STAGE(PG8_SA(1, 0), a_tile(uA, tbA + 1), voffA); PG8_STAGE(PG8_SB(1, 1), cB + hstepB + kstepB, voffB);
;         PG8_WAIT_V(6); PG8_BAR;
;     } else {
;         PG8_STAGE(PG8_SB(0, 0), cB, voffB); PG8_STAGE(PG8_SA(0, 0), cA, voffA); PG8_STAGE(PG8_SB(0, 1), cB + hstepB, voffB); PG8_STAGE(PG8_SA(0, 1), cA + hstepA, voffA);
;         if (wr == 1) PG8_BAR;
.LBB0_1155:
	s_or_b64 exec, exec, s[2:3]
	v_readlane_b32 s4, v252, 14
	v_readlane_b32 s5, v252, 15
	v_mov_b32_e32 v9, v0
	s_waitcnt lgkmcnt(0)
	v_cndmask_b32_e64 v2, 0, 1, s[4:5]
	v_cmp_ne_u32_e64 s[2:3], 1, v2
	s_barrier
	s_nop 0
	v_writelane_b32 v252, s2, 26
	s_andn2_b64 vcc, exec, s[4:5]
	v_readfirstlane_b32 s6, v9
	v_writelane_b32 v252, s3, 27
	s_cbranch_vccnz .LBB0_1171
	v_lshlrev_b32_e32 v2, 4, v9
	v_add_u32_e32 v3, 0x2000, v2
	v_ashrrev_i32_e32 v4, 31, v3
	v_lshrrev_b32_e32 v4, 22, v4
	v_add_u32_e32 v4, v3, v4
	v_ashrrev_i32_e32 v6, 10, v4
	v_mul_i32_i24_e32 v5, 0x400, v6
	v_sub_u32_e32 v3, v3, v5
	v_lshrrev_b32_e32 v5, 4, v3
	v_bitop3_b32 v3, v5, v3, 32 bitop3:0x6c
	v_ashrrev_i32_e32 v5, 31, v3
	v_lshrrev_b32_e32 v5, 26, v5
	v_add_u32_e32 v5, v3, v5
	v_ashrrev_i32_e32 v7, 6, v5
	v_and_b32_e32 v5, 0xc0, v5
	v_sub_u32_e32 v3, v3, v5
	v_mov_b32_e32 v5, 1
	v_lshlrev_b32_e32 v4, 5, v6
	v_ashrrev_i16_sdwa v3, v5, sext(v3) dst_sel:DWORD dst_unused:UNUSED_PAD src0_sel:DWORD src1_sel:BYTE_0
	v_and_b32_e32 v4, 32, v4
	v_bfe_i32 v8, v3, 0, 16
	v_add_u32_e32 v3, v4, v8
	v_lshlrev_b32_e32 v4, 3, v6
	v_and_b32_e32 v4, -16, v4
	v_add_u32_e32 v4, v7, v4
	v_lshlrev_b32_e32 v10, 7, v4
	v_lshl_add_u32 v130, v3, 1, v10
	s_movk_i32 s4, 0xf80
	v_mad_u64_u32 v[132:133], s[2:3], v4, s4, v[130:131]
	v_bfe_i32 v4, v9, 27, 1
	v_lshrrev_b32_e32 v4, 22, v4
	v_add_u32_e32 v4, v2, v4
	v_and_b32_e32 v4, 0xfffffc00, v4
	v_sub_u32_e32 v2, v2, v4
	v_lshrrev_b32_e32 v4, 4, v2
	v_bitop3_b32 v4, v4, v2, 32 bitop3:0x6c
	v_ashrrev_i32_e32 v2, 31, v2
	v_lshrrev_b32_e32 v2, 26, v2
	v_ashrrev_i32_e32 v3, 31, v9
	v_add_u32_e32 v2, v4, v2
	v_lshrrev_b32_e32 v3, 26, v3
	v_ashrrev_i32_e32 v11, 6, v2
	v_add_u32_e32 v3, v9, v3
	v_mul_i32_i24_e32 v2, 64, v11
	v_ashrrev_i32_e32 v10, 6, v3
	v_sub_u32_e32 v2, v4, v2
	v_lshlrev_b32_e32 v3, 5, v10
	v_ashrrev_i16_sdwa v2, v5, sext(v2) dst_sel:DWORD dst_unused:UNUSED_PAD src0_sel:DWORD src1_sel:BYTE_0
	v_and_b32_e32 v3, 32, v3
	v_bfe_i32 v12, v2, 0, 16
	v_add_u32_e32 v2, v3, v12
	v_lshlrev_b32_e32 v3, 3, v10
	v_and_b32_e32 v3, -16, v3
	v_add_u32_e32 v3, v11, v3
	v_readlane_b32 s8, v252, 19
	v_lshlrev_b32_e32 v4, 7, v3
	v_readlane_b32 s10, v252, 21
	v_lshl_add_u32 v134, v2, 1, v4
	v_readlane_b32 s11, v252, 22
	s_add_u32 s40, s10, 0x8900000
	v_mad_u64_u32 v[136:137], s[2:3], v3, s4, v[134:135]
	s_addc_u32 s41, s11, 0
	s_lshr_b32 s2, s70, 30
	s_add_i32 s2, s70, s2
	s_ashr_i32 s22, s2, 2
	s_sub_i32 s2, s91, s22
	s_lshl_b32 s2, s2, 2
	s_add_i32 s24, s2, s70
	s_ashr_i32 s8, s6, 6
	s_ashr_i32 s23, s22, 31
	s_ashr_i32 s25, s24, 31
	s_ashr_i32 s7, s6, 8
	s_lshl_b32 s42, s8, 10
	s_lshl_b64 s[2:3], s[22:23], 20
	s_lshl_b64 s[4:5], s[24:25], 20
	s_add_u32 s28, s40, s4
	s_addc_u32 s29, s41, s5
	s_add_i32 s25, s42, 0
	s_add_i32 m0, s25, 0x10000
	v_mov_b32_e32 v139, 0
	global_load_lds_dwordx4 v134, s[28:29]
	s_add_i32 m0, s25, 0x12000
	s_add_u32 s4, s28, 0x4000
	global_load_lds_dwordx4 v130, s[28:29]
	s_addc_u32 s5, s29, 0
	s_add_i32 m0, s25, 0x14000
	v_mov_b32_e32 v137, v139
	global_load_lds_dwordx4 v134, s[4:5]
	s_add_i32 m0, s25, 0x16000
	s_add_u32 s26, s59, s2
	s_addc_u32 s27, s62, s3
	s_add_i32 s43, s25, 0x2000
	global_load_lds_dwordx4 v130, s[4:5]
	s_mov_b32 m0, s25
	s_add_u32 s2, s26, 0x80000
	global_load_lds_dwordx4 v136, s[26:27]
	s_mov_b32 m0, s43
	s_addc_u32 s3, s27, 0
	s_add_i32 s44, s25, 0x4000
	global_load_lds_dwordx4 v132, s[26:27]
	s_mov_b32 m0, s44
	s_add_i32 s45, s25, 0x6000
	global_load_lds_dwordx4 v136, s[2:3]
	s_mov_b32 m0, s45
	v_mov_b32_e32 v133, v139
	global_load_lds_dwordx4 v132, s[2:3]
	s_cmp_eq_u32 s7, 1
	s_mov_b32 s46, 0
	v_mov_b32_e32 v135, v139
	v_mov_b32_e32 v131, v139
	s_mov_b64 s[4:5], 0x4000
	v_lshl_add_u64 v[2:3], s[26:27], 0, v[136:137]
	s_cselect_b64 s[2:3], -1, 0
	s_cmp_lg_u32 s7, 1
	v_lshl_add_u64 v[4:5], s[26:27], 0, v[132:133]
	v_readlane_b32 s9, v252, 20
	s_cbranch_scc1 .LBB0_1158
	s_setprio 1
	s_barrier

; #define PG8_WAIT_V(n) asm volatile("s_waitcnt vmcnt(" #n ")" ::: "memory")
; #define PG8_BAR __builtin_amdgcn_s_barrier()
; __device__ __forceinline__ unsigned xb_add(unsigned* p, unsigned v) { return __hip_atomic_fetch_add(p, v, __ATOMIC_RELAXED, __HIP_MEMORY_SCOPE_AGENT); }
; template <class Epi, class Sched, bool ABLK = false, bool ALIGN_EPI = true, bool SP2 = true, bool BBLK = true>
; __device__ __forceinline__ void gemm_phase(LAS unsigned char* lds, const Gemm g, const Sched& S, const Epi& E) {
;     ...
;     PG8_WAIT_V(0);
;     if constexpr (!ALIGN_EPI) { if (wr == 0) PG8_BAR; }
;     PG8_BAR;
; __device__ __forceinline__ void xcd_barrier(const XcdBarrier& b) {
;     asm volatile("s_waitcnt vmcnt(0)" ::: "memory");
;     __syncthreads();
;     if (threadIdx.x == 0) {
;         unsigned* bar = b.bar;
;         __builtin_amdgcn_s_waitcnt(0);
;         unsigned nloc = b.st[0], nx = b.st[1];
;         if (nloc == 0u) { xcd_barrier_complete(bar, b.x, nloc, nx); b.st[0] = nloc; b.st[1] = nx; }
;         const unsigned old = xb_add(&bar[XB_XSUB(b.x)], 1u);
;         const unsigned gen = old / nloc;
.LBB0_1171:
	s_waitcnt vmcnt(0)
	s_waitcnt vmcnt(0)
	s_setprio 0
	s_barrier
	s_and_saveexec_b64 s[2:3], s[92:93]
	s_cbranch_execz .LBB0_1223
	s_add_i32 s4, 0, 0x20000
	v_mov_b32_e32 v2, s4
	s_waitcnt vmcnt(0) expcnt(0) lgkmcnt(0)
	ds_read_b32 v4, v2
	s_add_i32 s4, 0, 0x20004
	v_mov_b32_e32 v2, s4
	ds_read_b32 v2, v2
	s_waitcnt lgkmcnt(1)
	v_cmp_ne_u32_e32 vcc, 0, v4
	s_cbranch_vccnz .LBB0_1187
	v_readlane_b32 s6, v252, 7
	v_readlane_b32 s7, v252, 8
	s_load_dwordx2 s[4:5], s[6:7], 0x4
	s_add_u32 s6, s68, 0x4200
	s_addc_u32 s7, s69, 0
	s_add_u32 s8, s68, 0x4400
	s_addc_u32 s9, s69, 0
	s_add_u32 s10, s68, 0x4500
	s_addc_u32 s11, s69, 0
	s_add_u32 s14, s68, 0x4600
	s_addc_u32 s15, s69, 0
	s_add_u32 s16, s68, 0x4700
	s_addc_u32 s17, s69, 0
	s_add_u32 s18, s68, 0x4800
	s_addc_u32 s19, s69, 0
	s_add_u32 s20, s68, 0x4900
	s_addc_u32 s21, s69, 0
	s_add_u32 s22, s68, 0x4a00
	s_addc_u32 s23, s69, 0
	s_add_u32 s24, s68, 0x4b00
	s_addc_u32 s25, s69, 0
	s_waitcnt lgkmcnt(0)
	s_mul_i32 s50, s4, s89
	s_add_u32 s4, s68, 0x4c00
	s_mul_i32 s50, s50, s5
	s_addc_u32 s5, s69, 0
	s_add_u32 s26, s68, 0x4d00
	s_addc_u32 s27, s69, 0
	s_add_u32 s28, s68, 0x4e00
	s_addc_u32 s29, s69, 0
	s_add_u32 s30, s68, 0x4f00
	s_addc_u32 s31, s69, 0
	s_add_u32 s34, s68, 0x5000
	s_addc_u32 s35, s69, 0
	s_add_u32 s36, s68, 0x5100
	s_addc_u32 s37, s69, 0
	s_add_u32 s40, s68, 0x5200
	s_addc_u32 s41, s69, 0
	s_add_u32 s42, s68, 0x5300
	s_addc_u32 s43, s69, 0
	s_mov_b32 s51, 1
	v_mov_b32_e32 v18, 0
	s_branch .LBB0_1175

; __device__ __forceinline__ int tid_fresh() { int t = threadIdx.x; asm volatile("" : "+v"(t)); return t; }
; #define PG8_STAGE(bufoff, gbase, voff) do { _Pragma("unroll") for (int _i = 0; _i < 2; ++_i) \
;         __builtin_amdgcn_global_load_lds((const unsigned*)((const char*)(gbase) + (voff)[_i]), (LAS unsigned*)(lds + (bufoff) + ldsw + _i * 8192), 16, 0, 0); } while (0)
; #define PG8_WAIT_V(n) asm volatile("s_waitcnt vmcnt(" #n ")" ::: "memory")
; #define PG8_BAR __builtin_amdgcn_s_barrier()
; template <class Epi, class Sched, bool ABLK = false, bool ALIGN_EPI = true, bool SP2 = true, bool BBLK = true>
; __device__ __forceinline__ void gemm_phase(LAS unsigned char* lds, const Gemm g, const Sched& S, const Epi& E) {
;     const int tid = tid_fresh(), wid = __builtin_amdgcn_readfirstlane(tid >> 6), lane = tid & 63, wr = wid >> 2, wc = wid & 3, fr = lane & 15, fq = lane >> 4;
;     unsigned voffA[2], voffB[2];
; #pragma unroll
;     for (int i = 0; i < 2; ++i) { int R, C; stage_rc(tid * 16 + i * 8192, R, C); const int r32 = Epi::PERM ? perm32(R & 31) : (R & 31);
;         const int Rb = Epi::ADJ ? 64 * (R >> 5) + r32 : (R & ~31) + r32;
;         voffA[i] = (unsigned)(R * (ABLK ? 64 : g.lda) + C) * 2u; voffB[i] = BBLK ? (unsigned)(R * 64 + C) * 2u : (unsigned)(Rb * g.ldb + C) * 2u; }
;     ...
;     const char* uA = a_unit(cur); int tbA = cur.k0 / BK;
;     const char* cA = a_tile(uA, tbA); const char* cB = (const char*)g.Bt + (size_t)cur.pn * tstepB + b_k0(cur.k0);
;     S.a_ready(cur);
;     if constexpr (SP2) {
;         PG8_STAGE(PG8_SB(0, 0), cB, voffB); PG8_STAGE(PG8_SB(0, 1), cB + hstepB, voffB); PG8_STAGE(PG8_SA(0, 0), cA, voffA); PG8_STAGE(PG8_SA(0, 1), cA + hstepA, voffA);
;         if (wr == 1) PG8_BAR;
;         PG8_WAIT_V(2); PG8_BAR;
;         PG8_STAGE(PG8_SB(1, 0), cB + kstepB, voffB); PG8_STAGE(PG8_SA(1, 0), a_tile(uA, tbA + 1), voffA); PG8_STAGE(PG8_SB(1, 1), cB + hstepB + kstepB, voffB);
;         PG8_WAIT_V(6); PG8_BAR;
;     } else {
;         PG8_STAGE(PG8_SB(0, 0), cB, voffB); PG8_STAGE(PG8_SA(0, 0), cA, voffA); PG8_STAGE(PG8_SB(0, 1), cB + hstepB, voffB); PG8_STAGE(PG8_SA(0, 1), cA + hstepA, voffA);
;         if (wr == 1) PG8_BAR;
.LBB0_1223:
	s_or_b64 exec, exec, s[2:3]
	v_mov_b32_e32 v4, v0
	s_waitcnt lgkmcnt(0)
	s_barrier
	v_readlane_b32 s4, v252, 19
	v_bfe_i32 v3, v4, 27, 1
	v_lshlrev_b32_e32 v6, 4, v4
	v_lshrrev_b32_e32 v3, 22, v3
	v_add_u32_e32 v3, v6, v3
	v_and_b32_e32 v3, 0xfffffc00, v3
	v_sub_u32_e32 v3, v6, v3
	v_lshrrev_b32_e32 v5, 4, v3
	v_bitop3_b32 v5, v5, v3, 32 bitop3:0x6c
	v_ashrrev_i32_e32 v3, 31, v3
	v_lshrrev_b32_e32 v3, 26, v3
	v_ashrrev_i32_e32 v2, 31, v4
	v_add_u32_e32 v3, v5, v3
	v_lshrrev_b32_e32 v2, 26, v2
	v_ashrrev_i32_e32 v3, 6, v3
	v_add_u32_e32 v2, v4, v2
	v_mul_i32_i24_e32 v9, 64, v3
	v_ashrrev_i32_e32 v2, 6, v2
	v_sub_u32_e32 v5, v5, v9
	v_mov_b32_e32 v9, 1
	v_lshlrev_b32_e32 v7, 3, v2
	v_lshlrev_b32_e32 v8, 5, v2
	v_ashrrev_i16_sdwa v5, v9, sext(v5) dst_sel:DWORD dst_unused:UNUSED_PAD src0_sel:DWORD src1_sel:BYTE_0
	v_and_b32_e32 v7, 0x1fffff0, v7
	v_and_b32_e32 v8, 32, v8
	v_bfe_i32 v5, v5, 0, 16
	v_add_u32_e32 v8, v8, v5
	v_add_lshl_u32 v7, v3, v7, 7
	v_lshl_add_u32 v130, v8, 1, v7
	v_add_u32_e32 v7, 0x2000, v6
	v_ashrrev_i32_e32 v6, 31, v7
	v_lshrrev_b32_e32 v6, 22, v6
	v_add_u32_e32 v6, v7, v6
	v_ashrrev_i32_e32 v6, 10, v6
	v_mul_i32_i24_e32 v8, 0x400, v6
	v_sub_u32_e32 v7, v7, v8
	v_lshrrev_b32_e32 v8, 4, v7
	v_bitop3_b32 v8, v8, v7, 32 bitop3:0x6c
	v_lshlrev_b32_e32 v7, 3, v6
	v_readlane_b32 s6, v252, 21
	v_and_b32_e32 v10, 0x1fffff0, v7
	v_ashrrev_i32_e32 v7, 31, v8
	v_readlane_b32 s5, v252, 20
	v_readlane_b32 s7, v252, 22
	s_add_u32 s30, s6, 0x10900000
	v_readfirstlane_b32 s4, v4
	v_lshrrev_b32_e32 v7, 26, v7
	s_addc_u32 s31, s7, 0
	s_ashr_i32 s5, s4, 6
	v_add_u32_e32 v11, v8, v7
	v_ashrrev_i32_e32 v7, 6, v11
	v_and_b32_e32 v11, 0xc0, v11
	s_ashr_i32 s6, s4, 8
	s_lshl_b32 s34, s5, 10
	v_readlane_b32 s2, v252, 16
	v_sub_u32_e32 v8, v8, v11
	s_add_u32 s22, s30, s2
	v_lshlrev_b32_e32 v12, 5, v6
	v_ashrrev_i16_sdwa v8, v9, sext(v8) dst_sel:DWORD dst_unused:UNUSED_PAD src0_sel:DWORD src1_sel:BYTE_0
	s_addc_u32 s23, s31, 0
	s_add_i32 s35, s34, 0
	v_and_b32_e32 v12, 32, v12
	v_bfe_i32 v8, v8, 0, 16
	s_add_i32 m0, s35, 0x10000
	v_add_u32_e32 v9, v12, v8
	v_add_lshl_u32 v10, v7, v10, 7
	global_load_lds_dwordx4 v130, s[22:23]
	s_add_i32 m0, s35, 0x12000
	v_lshl_add_u32 v132, v9, 1, v10
	s_add_u32 s2, s22, 0x4000
	global_load_lds_dwordx4 v132, s[22:23]
	s_addc_u32 s3, s23, 0
	s_add_i32 m0, s35, 0x14000
	v_mov_b32_e32 v131, 0
	global_load_lds_dwordx4 v130, s[2:3]
	s_add_i32 m0, s35, 0x16000
	s_mov_b32 s43, 0
	global_load_lds_dwordx4 v132, s[2:3]
	v_readlane_b32 s2, v252, 17
	v_readlane_b32 s3, v252, 18
	s_add_u32 s24, s1, s2
	s_addc_u32 s25, s33, s3
	s_add_i32 s36, s35, 0x2000
	s_mov_b32 m0, s35
	s_add_u32 s2, s24, 0x4000
	global_load_lds_dwordx4 v130, s[24:25]
	s_mov_b32 m0, s36
	s_addc_u32 s3, s25, 0
	s_add_i32 s37, s35, 0x4000
	global_load_lds_dwordx4 v132, s[24:25]
	s_mov_b32 m0, s37
	s_add_i32 s40, s35, 0x6000
	global_load_lds_dwordx4 v130, s[2:3]
	s_mov_b32 m0, s40
	s_cmp_eq_u32 s6, 1
	global_load_lds_dwordx4 v132, s[2:3]
	s_cselect_b64 s[2:3], -1, 0
	s_cmp_lg_u32 s6, 1
	v_mov_b32_e32 v133, v131
	s_cbranch_scc1 .LBB0_1225
	s_setprio 1
	s_barrier

; #define PG8_WAIT_V(n) asm volatile("s_waitcnt vmcnt(" #n ")" ::: "memory")
; #define PG8_BAR __builtin_amdgcn_s_barrier()
; __device__ __forceinline__ unsigned xb_add(unsigned* p, unsigned v) { return __hip_atomic_fetch_add(p, v, __ATOMIC_RELAXED, __HIP_MEMORY_SCOPE_AGENT); }
; template <class Epi, class Sched, bool ABLK = false, bool ALIGN_EPI = true, bool SP2 = true, bool BBLK = true>
; __device__ __forceinline__ void gemm_phase(LAS unsigned char* lds, const Gemm g, const Sched& S, const Epi& E) {
;     ...
;     PG8_WAIT_V(0);
;     if constexpr (!ALIGN_EPI) { if (wr == 0) PG8_BAR; }
;     PG8_BAR;
; __device__ __forceinline__ void xcd_barrier(const XcdBarrier& b) {
;     asm volatile("s_waitcnt vmcnt(0)" ::: "memory");
;     __syncthreads();
;     if (threadIdx.x == 0) {
;         unsigned* bar = b.bar;
;         __builtin_amdgcn_s_waitcnt(0);
;         unsigned nloc = b.st[0], nx = b.st[1];
;         if (nloc == 0u) { xcd_barrier_complete(bar, b.x, nloc, nx); b.st[0] = nloc; b.st[1] = nx; }
;         const unsigned old = xb_add(&bar[XB_XSUB(b.x)], 1u);
;         const unsigned gen = old / nloc;
.LBB0_1235:
	s_waitcnt vmcnt(0)
	s_barrier
	s_waitcnt vmcnt(0)
	s_waitcnt vmcnt(0)
	s_setprio 0
	s_barrier
	s_and_saveexec_b64 s[2:3], s[92:93]
	s_cbranch_execz .LBB0_1287
	s_add_i32 s1, 0, 0x20000
	v_mov_b32_e32 v2, s1
	s_waitcnt vmcnt(0) expcnt(0) lgkmcnt(0)
	ds_read_b32 v4, v2
	s_add_i32 s1, 0, 0x20004
	v_mov_b32_e32 v2, s1
	ds_read_b32 v2, v2
	s_waitcnt lgkmcnt(1)
	v_cmp_ne_u32_e32 vcc, 0, v4
	s_cbranch_vccnz .LBB0_1251
	v_readlane_b32 s6, v252, 7
	v_readlane_b32 s7, v252, 8
	s_load_dwordx2 s[4:5], s[6:7], 0x4
	s_add_u32 s6, s68, 0x4200
	s_addc_u32 s7, s69, 0
	s_add_u32 s8, s68, 0x4400
	s_addc_u32 s9, s69, 0
	s_add_u32 s10, s68, 0x4500
	s_addc_u32 s11, s69, 0
	s_add_u32 s12, s68, 0x4600
	s_addc_u32 s13, s69, 0
	s_add_u32 s14, s68, 0x4700
	s_addc_u32 s15, s69, 0
	s_add_u32 s16, s68, 0x4800
	s_addc_u32 s17, s69, 0
	s_add_u32 s18, s68, 0x4900
	s_addc_u32 s19, s69, 0
	s_add_u32 s20, s68, 0x4a00
	s_addc_u32 s21, s69, 0
	s_add_u32 s22, s68, 0x4b00
	s_addc_u32 s23, s69, 0
	s_waitcnt lgkmcnt(0)
	s_mul_i32 s1, s4, s89
	s_add_u32 s4, s68, 0x4c00
	s_mul_i32 s1, s1, s5
	s_addc_u32 s5, s69, 0
	s_add_u32 s24, s68, 0x4d00
	s_addc_u32 s25, s69, 0
	s_add_u32 s26, s68, 0x4e00
	s_addc_u32 s27, s69, 0
	s_add_u32 s28, s68, 0x4f00
	s_addc_u32 s29, s69, 0
	s_add_u32 s30, s68, 0x5000
	s_addc_u32 s31, s69, 0
	s_add_u32 s34, s68, 0x5100
	s_addc_u32 s35, s69, 0
	s_add_u32 s36, s68, 0x5200
	s_addc_u32 s37, s69, 0
	s_add_u32 s40, s68, 0x5300
	s_addc_u32 s41, s69, 0
	s_mov_b32 s33, 1
	v_mov_b32_e32 v18, 0
	s_branch .LBB0_1239

; __device__ __forceinline__ int tid_fresh() { int t = threadIdx.x; asm volatile("" : "+v"(t)); return t; }
; #define PG8_STAGE(bufoff, gbase, voff) do { _Pragma("unroll") for (int _i = 0; _i < 2; ++_i) \
;         __builtin_amdgcn_global_load_lds((const unsigned*)((const char*)(gbase) + (voff)[_i]), (LAS unsigned*)(lds + (bufoff) + ldsw + _i * 8192), 16, 0, 0); } while (0)
; #define PG8_WAIT_V(n) asm volatile("s_waitcnt vmcnt(" #n ")" ::: "memory")
; #define PG8_BAR __builtin_amdgcn_s_barrier()
; template <class Epi, class Sched, bool ABLK = false, bool ALIGN_EPI = true, bool SP2 = true, bool BBLK = true>
; __device__ __forceinline__ void gemm_phase(LAS unsigned char* lds, const Gemm g, const Sched& S, const Epi& E) {
;     const int tid = tid_fresh(), wid = __builtin_amdgcn_readfirstlane(tid >> 6), lane = tid & 63, wr = wid >> 2, wc = wid & 3, fr = lane & 15, fq = lane >> 4;
;     unsigned voffA[2], voffB[2];
; #pragma unroll
;     for (int i = 0; i < 2; ++i) { int R, C; stage_rc(tid * 16 + i * 8192, R, C); const int r32 = Epi::PERM ? perm32(R & 31) : (R & 31);
;         const int Rb = Epi::ADJ ? 64 * (R >> 5) + r32 : (R & ~31) + r32;
;         voffA[i] = (unsigned)(R * (ABLK ? 64 : g.lda) + C) * 2u; voffB[i] = BBLK ? (unsigned)(R * 64 + C) * 2u : (unsigned)(Rb * g.ldb + C) * 2u; }
;     ...
;     const char* uA = a_unit(cur); int tbA = cur.k0 / BK;
;     const char* cA = a_tile(uA, tbA); const char* cB = (const char*)g.Bt + (size_t)cur.pn * tstepB + b_k0(cur.k0);
;     S.a_ready(cur);
;     if constexpr (SP2) {
;         PG8_STAGE(PG8_SB(0, 0), cB, voffB); PG8_STAGE(PG8_SB(0, 1), cB + hstepB, voffB); PG8_STAGE(PG8_SA(0, 0), cA, voffA); PG8_STAGE(PG8_SA(0, 1), cA + hstepA, voffA);
;         if (wr == 1) PG8_BAR;
;         PG8_WAIT_V(2); PG8_BAR;
;         PG8_STAGE(PG8_SB(1, 0), cB + kstepB, voffB); PG8_STAGE(PG8_SA(1, 0), a_tile(uA, tbA + 1), voffA); PG8_STAGE(PG8_SB(1, 1), cB + hstepB + kstepB, voffB);
;         PG8_WAIT_V(6); PG8_BAR;
;     } else {
;         PG8_STAGE(PG8_SB(0, 0), cB, voffB); PG8_STAGE(PG8_SA(0, 0), cA, voffA); PG8_STAGE(PG8_SB(0, 1), cB + hstepB, voffB); PG8_STAGE(PG8_SA(0, 1), cA + hstepA, voffA);
;         if (wr == 1) PG8_BAR;
.LBB0_1346:
	s_or_b64 exec, exec, s[2:3]
	s_add_u32 s76, s68, 0x1b900000
	s_addc_u32 s33, s69, 0
	s_add_u32 s90, s68, 0x1e100000
	s_addc_u32 s91, s69, 0
	v_readlane_b32 s2, v252, 26
	s_add_u32 s62, s68, 0x23100000
	v_mov_b32_e32 v9, v0
	v_readlane_b32 s3, v252, 27
	s_waitcnt lgkmcnt(0)
	s_barrier
	s_addc_u32 s83, s69, 0
	s_and_b64 vcc, exec, s[2:3]
	v_readfirstlane_b32 s4, v9
	s_cbranch_vccnz .LBB0_1366
	v_lshlrev_b32_e32 v2, 4, v9
	v_add_u32_e32 v3, 0x2000, v2
	v_ashrrev_i32_e32 v4, 31, v3
	v_lshrrev_b32_e32 v4, 22, v4
	v_add_u32_e32 v4, v3, v4
	v_ashrrev_i32_e32 v6, 10, v4
	v_mul_i32_i24_e32 v5, 0x400, v6
	v_sub_u32_e32 v3, v3, v5
	v_lshrrev_b32_e32 v5, 4, v3
	v_bitop3_b32 v3, v5, v3, 32 bitop3:0x6c
	v_ashrrev_i32_e32 v5, 31, v3
	v_lshrrev_b32_e32 v5, 26, v5
	v_add_u32_e32 v5, v3, v5
	v_ashrrev_i32_e32 v7, 6, v5
	v_and_b32_e32 v5, 0xc0, v5
	v_sub_u32_e32 v3, v3, v5
	v_mov_b32_e32 v5, 1
	v_lshlrev_b32_e32 v4, 5, v6
	v_ashrrev_i16_sdwa v3, v5, sext(v3) dst_sel:DWORD dst_unused:UNUSED_PAD src0_sel:DWORD src1_sel:BYTE_0
	v_and_b32_e32 v4, 32, v4
	v_bfe_i32 v8, v3, 0, 16
	v_add_u32_e32 v3, v4, v8
	v_lshlrev_b32_e32 v4, 3, v6
	v_and_b32_e32 v4, -16, v4
	v_add_u32_e32 v4, v7, v4
	v_lshlrev_b32_e32 v10, 7, v4
	v_lshl_add_u32 v130, v3, 1, v10
	s_movk_i32 s6, 0xf80
	v_mad_u64_u32 v[132:133], s[2:3], v4, s6, v[130:131]
	v_bfe_i32 v4, v9, 27, 1
	v_lshrrev_b32_e32 v4, 22, v4
	v_add_u32_e32 v4, v2, v4
	v_and_b32_e32 v4, 0xfffffc00, v4
	v_sub_u32_e32 v2, v2, v4
	v_lshrrev_b32_e32 v4, 4, v2
	v_bitop3_b32 v4, v4, v2, 32 bitop3:0x6c
	v_ashrrev_i32_e32 v2, 31, v2
	v_lshrrev_b32_e32 v2, 26, v2
	v_ashrrev_i32_e32 v3, 31, v9
	v_add_u32_e32 v2, v4, v2
	v_lshrrev_b32_e32 v3, 26, v3
	v_ashrrev_i32_e32 v11, 6, v2
	v_add_u32_e32 v3, v9, v3
	v_mul_i32_i24_e32 v2, 64, v11
	v_ashrrev_i32_e32 v10, 6, v3
	v_sub_u32_e32 v2, v4, v2
	v_lshlrev_b32_e32 v3, 5, v10
	v_ashrrev_i16_sdwa v2, v5, sext(v2) dst_sel:DWORD dst_unused:UNUSED_PAD src0_sel:DWORD src1_sel:BYTE_0
	v_and_b32_e32 v3, 32, v3
	v_bfe_i32 v12, v2, 0, 16
	v_add_u32_e32 v2, v3, v12
	v_lshlrev_b32_e32 v3, 3, v10
	v_and_b32_e32 v3, -16, v3
	v_add_u32_e32 v3, v11, v3
	v_lshlrev_b32_e32 v4, 7, v3
	v_lshl_add_u32 v134, v2, 1, v4
	s_add_u32 s1, s68, 0x4100000
	v_mad_u64_u32 v[136:137], s[2:3], v3, s6, v[134:135]
	s_addc_u32 s48, s69, 0
	s_lshr_b32 s2, s70, 30
	s_add_i32 s2, s70, s2
	s_ashr_i32 s34, s2, 2
	v_readlane_b32 s2, v252, 23
	s_sub_i32 s2, s2, s34
	s_lshl_b32 s2, s2, 2
	s_add_i32 s30, s2, s70
	s_ashr_i32 s8, s4, 6
	s_ashr_i32 s35, s34, 31
	s_ashr_i32 s31, s30, 31
	s_ashr_i32 s5, s4, 8
	s_lshl_b32 s49, s8, 10
	s_lshl_b64 s[2:3], s[34:35], 20
	s_lshl_b64 s[6:7], s[30:31], 20
	s_add_u32 s40, s1, s6
	s_addc_u32 s41, s48, s7
	s_add_i32 s31, s49, 0
	s_add_i32 m0, s31, 0x10000
	v_mov_b32_e32 v139, 0
	global_load_lds_dwordx4 v134, s[40:41]
	s_add_i32 m0, s31, 0x12000
	s_add_u32 s6, s40, 0x4000
	global_load_lds_dwordx4 v130, s[40:41]
	s_addc_u32 s7, s41, 0
	s_add_i32 m0, s31, 0x14000
	v_mov_b32_e32 v137, v139
	global_load_lds_dwordx4 v134, s[6:7]
	s_add_i32 m0, s31, 0x16000
	s_add_u32 s36, s76, s2
	s_addc_u32 s37, s33, s3
	s_add_i32 s35, s31, 0x2000
	global_load_lds_dwordx4 v130, s[6:7]
	s_mov_b32 m0, s31
	s_add_u32 s2, s36, 0x80000
	global_load_lds_dwordx4 v136, s[36:37]
	s_mov_b32 m0, s35
	s_addc_u32 s3, s37, 0
	s_add_i32 s50, s31, 0x4000
	global_load_lds_dwordx4 v132, s[36:37]
	s_mov_b32 m0, s50
	s_add_i32 s51, s31, 0x6000
	global_load_lds_dwordx4 v136, s[2:3]
	s_mov_b32 m0, s51
	v_mov_b32_e32 v133, v139
	global_load_lds_dwordx4 v132, s[2:3]
	s_cmp_eq_u32 s5, 1
	s_mov_b32 s52, 0
	v_mov_b32_e32 v135, v139
	v_mov_b32_e32 v131, v139
	v_lshl_add_u64 v[4:5], s[36:37], 0, v[136:137]
	v_lshl_add_u64 v[2:3], s[36:37], 0, v[132:133]
	s_cselect_b64 s[2:3], -1, 0
	s_cmp_lg_u32 s5, 1
	s_mov_b64 s[6:7], 0x80000
	s_cbranch_scc1 .LBB0_1349
	s_setprio 1
	s_barrier

; #define PG8_WAIT_V(n) asm volatile("s_waitcnt vmcnt(" #n ")" ::: "memory")
; #define PG8_BAR __builtin_amdgcn_s_barrier()
; __device__ __forceinline__ unsigned xb_add(unsigned* p, unsigned v) { return __hip_atomic_fetch_add(p, v, __ATOMIC_RELAXED, __HIP_MEMORY_SCOPE_AGENT); }
; template <class Epi, class Sched, bool ABLK = false, bool ALIGN_EPI = true, bool SP2 = true, bool BBLK = true>
; __device__ __forceinline__ void gemm_phase(LAS unsigned char* lds, const Gemm g, const Sched& S, const Epi& E) {
;     ...
;     PG8_WAIT_V(0);
;     if constexpr (!ALIGN_EPI) { if (wr == 0) PG8_BAR; }
;     PG8_BAR;
; __device__ __forceinline__ void xcd_barrier(const XcdBarrier& b) {
;     asm volatile("s_waitcnt vmcnt(0)" ::: "memory");
;     __syncthreads();
;     if (threadIdx.x == 0) {
;         unsigned* bar = b.bar;
;         __builtin_amdgcn_s_waitcnt(0);
;         unsigned nloc = b.st[0], nx = b.st[1];
;         if (nloc == 0u) { xcd_barrier_complete(bar, b.x, nloc, nx); b.st[0] = nloc; b.st[1] = nx; }
;         const unsigned old = xb_add(&bar[XB_XSUB(b.x)], 1u);
;         const unsigned gen = old / nloc;
.LBB0_1366:
	s_waitcnt vmcnt(0)
	s_waitcnt vmcnt(0)
	s_setprio 0
	s_barrier
	s_and_saveexec_b64 s[2:3], s[92:93]
	s_cbranch_execz .LBB0_1418
	s_add_i32 s1, 0, 0x20000
	v_mov_b32_e32 v2, s1
	s_waitcnt vmcnt(0) expcnt(0) lgkmcnt(0)
	ds_read_b32 v4, v2
	s_add_i32 s1, 0, 0x20004
	v_mov_b32_e32 v2, s1
	ds_read_b32 v2, v2
	s_waitcnt lgkmcnt(1)
	v_cmp_ne_u32_e32 vcc, 0, v4
	s_cbranch_vccnz .LBB0_1382
	v_readlane_b32 s6, v252, 7
	v_readlane_b32 s7, v252, 8
	s_load_dwordx2 s[4:5], s[6:7], 0x4
	s_add_u32 s6, s68, 0x4200
	s_addc_u32 s7, s69, 0
	s_add_u32 s8, s68, 0x4400
	s_addc_u32 s9, s69, 0
	s_add_u32 s10, s68, 0x4500
	s_addc_u32 s11, s69, 0
	s_add_u32 s12, s68, 0x4600
	s_addc_u32 s13, s69, 0
	s_add_u32 s14, s68, 0x4700
	s_addc_u32 s15, s69, 0
	s_add_u32 s16, s68, 0x4800
	s_addc_u32 s17, s69, 0
	s_add_u32 s18, s68, 0x4900
	s_addc_u32 s19, s69, 0
	s_add_u32 s20, s68, 0x4a00
	s_addc_u32 s21, s69, 0
	s_add_u32 s22, s68, 0x4b00
	s_addc_u32 s23, s69, 0
	s_waitcnt lgkmcnt(0)
	s_mul_i32 s1, s4, s89
	s_add_u32 s4, s68, 0x4c00
	s_mul_i32 s1, s1, s5
	s_addc_u32 s5, s69, 0
	s_add_u32 s24, s68, 0x4d00
	s_addc_u32 s25, s69, 0
	s_add_u32 s26, s68, 0x4e00
	s_addc_u32 s27, s69, 0
	s_add_u32 s28, s68, 0x4f00
	s_addc_u32 s29, s69, 0
	s_add_u32 s30, s68, 0x5000
	s_addc_u32 s31, s69, 0
	s_add_u32 s34, s68, 0x5100
	s_addc_u32 s35, s69, 0
	s_add_u32 s36, s68, 0x5200
	s_addc_u32 s37, s69, 0
	s_add_u32 s40, s68, 0x5300
	s_addc_u32 s41, s69, 0
	s_mov_b32 s48, 1
	v_mov_b32_e32 v18, 0
	s_branch .LBB0_1370

; __device__ __forceinline__ int tid_fresh() { int t = threadIdx.x; asm volatile("" : "+v"(t)); return t; }
; #define PG8_STAGE(bufoff, gbase, voff) do { _Pragma("unroll") for (int _i = 0; _i < 2; ++_i) \
;         __builtin_amdgcn_global_load_lds((const unsigned*)((const char*)(gbase) + (voff)[_i]), (LAS unsigned*)(lds + (bufoff) + ldsw + _i * 8192), 16, 0, 0); } while (0)
; #define PG8_WAIT_V(n) asm volatile("s_waitcnt vmcnt(" #n ")" ::: "memory")
; #define PG8_BAR __builtin_amdgcn_s_barrier()
; template <class Epi, class Sched, bool ABLK = false, bool ALIGN_EPI = true, bool SP2 = true, bool BBLK = true>
; __device__ __forceinline__ void gemm_phase(LAS unsigned char* lds, const Gemm g, const Sched& S, const Epi& E) {
;     const int tid = tid_fresh(), wid = __builtin_amdgcn_readfirstlane(tid >> 6), lane = tid & 63, wr = wid >> 2, wc = wid & 3, fr = lane & 15, fq = lane >> 4;
;     unsigned voffA[2], voffB[2];
; #pragma unroll
;     for (int i = 0; i < 2; ++i) { int R, C; stage_rc(tid * 16 + i * 8192, R, C); const int r32 = Epi::PERM ? perm32(R & 31) : (R & 31);
;         const int Rb = Epi::ADJ ? 64 * (R >> 5) + r32 : (R & ~31) + r32;
;         voffA[i] = (unsigned)(R * (ABLK ? 64 : g.lda) + C) * 2u; voffB[i] = BBLK ? (unsigned)(R * 64 + C) * 2u : (unsigned)(Rb * g.ldb + C) * 2u; }
;     ...
;     const char* uA = a_unit(cur); int tbA = cur.k0 / BK;
;     const char* cA = a_tile(uA, tbA); const char* cB = (const char*)g.Bt + (size_t)cur.pn * tstepB + b_k0(cur.k0);
;     S.a_ready(cur);
;     if constexpr (SP2) {
;         PG8_STAGE(PG8_SB(0, 0), cB, voffB); PG8_STAGE(PG8_SB(0, 1), cB + hstepB, voffB); PG8_STAGE(PG8_SA(0, 0), cA, voffA); PG8_STAGE(PG8_SA(0, 1), cA + hstepA, voffA);
;         if (wr == 1) PG8_BAR;
;         PG8_WAIT_V(2); PG8_BAR;
;         PG8_STAGE(PG8_SB(1, 0), cB + kstepB, voffB); PG8_STAGE(PG8_SA(1, 0), a_tile(uA, tbA + 1), voffA); PG8_STAGE(PG8_SB(1, 1), cB + hstepB + kstepB, voffB);
;         PG8_WAIT_V(6); PG8_BAR;
;     } else {
;         PG8_STAGE(PG8_SB(0, 0), cB, voffB); PG8_STAGE(PG8_SA(0, 0), cA, voffA); PG8_STAGE(PG8_SB(0, 1), cB + hstepB, voffB); PG8_STAGE(PG8_SA(0, 1), cA + hstepA, voffA);
;         if (wr == 1) PG8_BAR;
.LBB0_1710:
	s_or_b64 exec, exec, s[2:3]
	s_waitcnt vmcnt(2)
	v_mov_b32_e32 v7, v0
	s_waitcnt lgkmcnt(0)
	s_barrier
	s_movk_i32 s6, 0xf080
	v_ashrrev_i32_e32 v2, 31, v7
	v_lshrrev_b32_e32 v2, 26, v2
	v_add_u32_e32 v2, v7, v2
	v_ashrrev_i32_e32 v6, 6, v2
	v_bfe_i32 v2, v7, 27, 1
	v_lshlrev_b32_e32 v1, 4, v7
	v_lshrrev_b32_e32 v2, 22, v2
	v_add_u32_e32 v2, v1, v2
	v_and_b32_e32 v2, 0xfffffc00, v2
	v_sub_u32_e32 v2, v1, v2
	v_lshrrev_b32_e32 v3, 4, v2
	v_bitop3_b32 v3, v3, v2, 32 bitop3:0x6c
	v_ashrrev_i32_e32 v2, 31, v2
	v_lshrrev_b32_e32 v2, 26, v2
	v_add_u32_e32 v2, v3, v2
	v_ashrrev_i32_e32 v8, 6, v2
	v_lshlrev_b32_e32 v4, 3, v6
	v_mul_i32_i24_e32 v5, 64, v8
	v_and_b32_e32 v4, -16, v4
	v_sub_u32_e32 v3, v3, v5
	v_mov_b32_e32 v5, 1
	v_add_u32_e32 v2, v8, v4
	v_lshlrev_b32_e32 v4, 5, v6
	v_ashrrev_i16_sdwa v3, v5, sext(v3) dst_sel:DWORD dst_unused:UNUSED_PAD src0_sel:DWORD src1_sel:BYTE_0
	v_and_b32_e32 v4, 32, v4
	v_bfe_i32 v9, v3, 0, 16
	v_add_u32_e32 v3, v4, v9
	v_lshlrev_b32_e32 v4, 12, v2
	v_lshl_add_u32 v130, v3, 1, v4
	v_add_u32_e32 v1, 0x2000, v1
	v_mad_u64_u32 v[132:133], s[2:3], v2, s6, v[130:131]
	v_ashrrev_i32_e32 v2, 31, v1
	v_lshrrev_b32_e32 v2, 22, v2
	v_add_u32_e32 v2, v1, v2
	s_waitcnt vmcnt(1)
	v_ashrrev_i32_e32 v10, 10, v2
	v_mul_i32_i24_e32 v2, 0x400, v10
	v_sub_u32_e32 v1, v1, v2
	v_lshrrev_b32_e32 v2, 4, v1
	v_bitop3_b32 v1, v2, v1, 32 bitop3:0x6c
	v_ashrrev_i32_e32 v3, 31, v1
	v_lshrrev_b32_e32 v3, 26, v3
	v_add_u32_e32 v3, v1, v3
	v_ashrrev_i32_e32 v11, 6, v3
	v_and_b32_e32 v3, 0xc0, v3
	v_lshlrev_b32_e32 v2, 3, v10
	v_sub_u32_e32 v1, v1, v3
	s_add_u32 s1, s68, 0x2d100000
	v_and_b32_e32 v2, -16, v2
	v_lshlrev_b32_e32 v4, 5, v10
	v_ashrrev_i16_sdwa v1, v5, sext(v1) dst_sel:DWORD dst_unused:UNUSED_PAD src0_sel:DWORD src1_sel:BYTE_0
	s_addc_u32 s36, s69, 0
	v_add_u32_e32 v2, v11, v2
	v_and_b32_e32 v4, 32, v4
	v_bfe_i32 v12, v1, 0, 16
	s_add_u32 s37, s68, 0x6100000
	v_readfirstlane_b32 s4, v7
	v_add_u32_e32 v1, v4, v12
	v_lshlrev_b32_e32 v3, 12, v2
	s_addc_u32 s38, s69, 0
	s_ashr_i32 s5, s4, 6
	v_lshl_add_u32 v134, v1, 1, v3
	v_mad_u64_u32 v[136:137], s[2:3], v2, s6, v[134:135]
	s_ashr_i32 s6, s4, 8
	s_lshl_b32 s39, s5, 10
	s_add_u32 s26, s37, s97
	s_addc_u32 s27, s38, 0
	s_add_i32 s40, s39, 0
	s_add_i32 m0, s40, 0x10000
	v_mov_b32_e32 v133, 0
	global_load_lds_dwordx4 v132, s[26:27]
	s_add_i32 m0, s40, 0x12000
	s_add_u32 s2, s26, 0x4000
	global_load_lds_dwordx4 v136, s[26:27]
	s_addc_u32 s3, s27, 0
	s_add_i32 m0, s40, 0x14000
	v_mov_b32_e32 v131, v133
	global_load_lds_dwordx4 v132, s[2:3]
	s_add_i32 m0, s40, 0x16000
	v_mov_b32_e32 v135, v133
	global_load_lds_dwordx4 v136, s[2:3]
	v_readlane_b32 s2, v252, 24
	v_readlane_b32 s3, v252, 25
	s_add_u32 s28, s1, s2
	s_addc_u32 s29, s36, s3
	s_add_i32 s41, s40, 0x2000
	s_mov_b32 m0, s40
	s_add_u32 s2, s28, 0x80000
	global_load_lds_dwordx4 v130, s[28:29]
	s_mov_b32 m0, s41
	s_addc_u32 s3, s29, 0
	s_add_i32 s42, s40, 0x4000
	global_load_lds_dwordx4 v134, s[28:29]
	s_mov_b32 m0, s42
	s_add_i32 s43, s40, 0x6000
	global_load_lds_dwordx4 v130, s[2:3]
	s_mov_b32 m0, s43
	s_cmp_eq_u32 s6, 1
	global_load_lds_dwordx4 v134, s[2:3]
	s_mov_b32 s47, 32
	s_mov_b32 s46, 0
	v_mov_b32_e32 v137, v133
	v_lshl_add_u64 v[2:3], s[28:29], 0, v[130:131]
	s_cselect_b64 s[2:3], -1, 0
	s_cmp_lg_u32 s6, 1
	v_lshl_add_u64 v[4:5], s[28:29], 0, v[134:135]
	s_cbranch_scc1 .LBB0_1712
	s_setprio 1
	s_barrier

; #define PG8_WAIT_V(n) asm volatile("s_waitcnt vmcnt(" #n ")" ::: "memory")
; #define PG8_BAR __builtin_amdgcn_s_barrier()
; __device__ __forceinline__ unsigned xb_add(unsigned* p, unsigned v) { return __hip_atomic_fetch_add(p, v, __ATOMIC_RELAXED, __HIP_MEMORY_SCOPE_AGENT); }
; template <class Epi, class Sched, bool ABLK = false, bool ALIGN_EPI = true, bool SP2 = true, bool BBLK = true>
; __device__ __forceinline__ void gemm_phase(LAS unsigned char* lds, const Gemm g, const Sched& S, const Epi& E) {
;     ...
;     PG8_WAIT_V(0);
;     if constexpr (!ALIGN_EPI) { if (wr == 0) PG8_BAR; }
;     PG8_BAR;
; __device__ __forceinline__ void xcd_barrier(const XcdBarrier& b) {
;     asm volatile("s_waitcnt vmcnt(0)" ::: "memory");
;     __syncthreads();
;     if (threadIdx.x == 0) {
;         unsigned* bar = b.bar;
;         __builtin_amdgcn_s_waitcnt(0);
;         unsigned nloc = b.st[0], nx = b.st[1];
;         if (nloc == 0u) { xcd_barrier_complete(bar, b.x, nloc, nx); b.st[0] = nloc; b.st[1] = nx; }
;         const unsigned old = xb_add(&bar[XB_XSUB(b.x)], 1u);
;         const unsigned gen = old / nloc;
.LBB0_1722:
	s_waitcnt vmcnt(0)
	s_barrier
	s_waitcnt vmcnt(0)
	s_waitcnt vmcnt(0)
	s_setprio 0
	s_barrier
	s_and_saveexec_b64 s[2:3], s[92:93]
	s_cbranch_execz .LBB0_1774
	s_add_i32 s1, 0, 0x20000
	v_mov_b32_e32 v1, s1
	s_waitcnt vmcnt(0) expcnt(0) lgkmcnt(0)
	ds_read_b32 v3, v1
	s_add_i32 s1, 0, 0x20004
	v_mov_b32_e32 v1, s1
	ds_read_b32 v1, v1
	s_waitcnt lgkmcnt(1)
	v_cmp_ne_u32_e32 vcc, 0, v3
	s_cbranch_vccnz .LBB0_1738
	v_readlane_b32 s6, v252, 7
	v_readlane_b32 s7, v252, 8
	s_load_dwordx2 s[4:5], s[6:7], 0x4
	s_add_u32 s6, s68, 0x4200
	s_addc_u32 s7, s69, 0
	s_add_u32 s8, s68, 0x4400
	s_addc_u32 s9, s69, 0
	s_add_u32 s10, s68, 0x4500
	s_addc_u32 s11, s69, 0
	s_add_u32 s14, s68, 0x4600
	s_addc_u32 s15, s69, 0
	s_add_u32 s16, s68, 0x4700
	s_addc_u32 s17, s69, 0
	s_add_u32 s18, s68, 0x4800
	s_addc_u32 s19, s69, 0
	s_add_u32 s20, s68, 0x4900
	s_addc_u32 s21, s69, 0
	s_add_u32 s22, s68, 0x4a00
	s_addc_u32 s23, s69, 0
	s_add_u32 s24, s68, 0x4b00
	s_addc_u32 s25, s69, 0
	s_waitcnt lgkmcnt(0)
	s_mul_i32 s1, s4, s89
	s_add_u32 s4, s68, 0x4c00
	s_mul_i32 s1, s1, s5
	s_addc_u32 s5, s69, 0
	s_add_u32 s26, s68, 0x4d00
	s_addc_u32 s27, s69, 0
	s_add_u32 s28, s68, 0x4e00
	s_addc_u32 s29, s69, 0
	s_add_u32 s30, s68, 0x4f00
	s_addc_u32 s31, s69, 0
	s_add_u32 s34, s68, 0x5000
	s_addc_u32 s35, s69, 0
	s_add_u32 s36, s68, 0x5100
	s_addc_u32 s37, s69, 0
	s_add_u32 s38, s68, 0x5200
	s_addc_u32 s39, s69, 0
	s_add_u32 s40, s68, 0x5300
	s_addc_u32 s41, s69, 0
	s_mov_b32 s48, 1
	v_mov_b32_e32 v17, 0
	s_branch .LBB0_1726

; __device__ __forceinline__ int tid_fresh() { int t = threadIdx.x; asm volatile("" : "+v"(t)); return t; }
; #define PG8_STAGE(bufoff, gbase, voff) do { _Pragma("unroll") for (int _i = 0; _i < 2; ++_i) \
;         __builtin_amdgcn_global_load_lds((const unsigned*)((const char*)(gbase) + (voff)[_i]), (LAS unsigned*)(lds + (bufoff) + ldsw + _i * 8192), 16, 0, 0); } while (0)
; #define PG8_WAIT_V(n) asm volatile("s_waitcnt vmcnt(" #n ")" ::: "memory")
; #define PG8_BAR __builtin_amdgcn_s_barrier()
; template <class Epi, class Sched, bool ABLK = false, bool ALIGN_EPI = true, bool SP2 = true, bool BBLK = true>
; __device__ __forceinline__ void gemm_phase(LAS unsigned char* lds, const Gemm g, const Sched& S, const Epi& E) {
;     const int tid = tid_fresh(), wid = __builtin_amdgcn_readfirstlane(tid >> 6), lane = tid & 63, wr = wid >> 2, wc = wid & 3, fr = lane & 15, fq = lane >> 4;
;     unsigned voffA[2], voffB[2];
; #pragma unroll
;     for (int i = 0; i < 2; ++i) { int R, C; stage_rc(tid * 16 + i * 8192, R, C); const int r32 = Epi::PERM ? perm32(R & 31) : (R & 31);
;         const int Rb = Epi::ADJ ? 64 * (R >> 5) + r32 : (R & ~31) + r32;
;         voffA[i] = (unsigned)(R * (ABLK ? 64 : g.lda) + C) * 2u; voffB[i] = BBLK ? (unsigned)(R * 64 + C) * 2u : (unsigned)(Rb * g.ldb + C) * 2u; }
;     ...
;     const char* uA = a_unit(cur); int tbA = cur.k0 / BK;
;     const char* cA = a_tile(uA, tbA); const char* cB = (const char*)g.Bt + (size_t)cur.pn * tstepB + b_k0(cur.k0);
;     S.a_ready(cur);
;     if constexpr (SP2) {
;         PG8_STAGE(PG8_SB(0, 0), cB, voffB); PG8_STAGE(PG8_SB(0, 1), cB + hstepB, voffB); PG8_STAGE(PG8_SA(0, 0), cA, voffA); PG8_STAGE(PG8_SA(0, 1), cA + hstepA, voffA);
;         if (wr == 1) PG8_BAR;
;         PG8_WAIT_V(2); PG8_BAR;
;         PG8_STAGE(PG8_SB(1, 0), cB + kstepB, voffB); PG8_STAGE(PG8_SA(1, 0), a_tile(uA, tbA + 1), voffA); PG8_STAGE(PG8_SB(1, 1), cB + hstepB + kstepB, voffB);
;         PG8_WAIT_V(6); PG8_BAR;
;     } else {
;         PG8_STAGE(PG8_SB(0, 0), cB, voffB); PG8_STAGE(PG8_SA(0, 0), cA, voffA); PG8_STAGE(PG8_SB(0, 1), cB + hstepB, voffB); PG8_STAGE(PG8_SA(0, 1), cA + hstepA, voffA);
;         if (wr == 1) PG8_BAR;
.LBB0_1833:
	s_or_b64 exec, exec, s[2:3]
	v_readlane_b32 s2, v252, 26
	s_waitcnt lgkmcnt(0)
	v_mov_b32_e32 v1, v0
	v_readlane_b32 s3, v252, 27
	s_barrier
	s_and_b64 vcc, exec, s[2:3]
	v_readfirstlane_b32 s6, v1
	s_cbranch_vccnz .LBB0_1849
	v_lshlrev_b32_e32 v2, 4, v1
	v_add_u32_e32 v3, 0x2000, v2
	v_ashrrev_i32_e32 v4, 31, v3
	v_lshrrev_b32_e32 v4, 22, v4
	v_add_u32_e32 v4, v3, v4
	v_ashrrev_i32_e32 v6, 10, v4
	v_mul_i32_i24_e32 v5, 0x400, v6
	v_sub_u32_e32 v3, v3, v5
	v_lshrrev_b32_e32 v5, 4, v3
	v_bitop3_b32 v3, v5, v3, 32 bitop3:0x6c
	v_ashrrev_i32_e32 v5, 31, v3
	v_lshrrev_b32_e32 v5, 26, v5
	v_add_u32_e32 v5, v3, v5
	v_ashrrev_i32_e32 v7, 6, v5
	v_and_b32_e32 v5, 0xc0, v5
	v_sub_u32_e32 v3, v3, v5
	v_mov_b32_e32 v5, 1
	v_lshlrev_b32_e32 v4, 5, v6
	v_ashrrev_i16_sdwa v3, v5, sext(v3) dst_sel:DWORD dst_unused:UNUSED_PAD src0_sel:DWORD src1_sel:BYTE_0
	v_and_b32_e32 v4, 32, v4
	v_bfe_i32 v8, v3, 0, 16
	v_add_u32_e32 v3, v4, v8
	v_lshlrev_b32_e32 v4, 3, v6
	v_and_b32_e32 v4, -16, v4
	v_add_u32_e32 v4, v7, v4
	v_lshlrev_b32_e32 v9, 7, v4
	v_lshl_add_u32 v130, v3, 1, v9
	s_movk_i32 s4, 0xf80
	v_mad_u64_u32 v[132:133], s[2:3], v4, s4, v[130:131]
	v_bfe_i32 v4, v1, 27, 1
	v_lshrrev_b32_e32 v4, 22, v4
	v_add_u32_e32 v4, v2, v4
	v_and_b32_e32 v4, 0xfffffc00, v4
	v_sub_u32_e32 v2, v2, v4
	v_lshrrev_b32_e32 v4, 4, v2
	v_bitop3_b32 v4, v4, v2, 32 bitop3:0x6c
	v_ashrrev_i32_e32 v2, 31, v2
	v_lshrrev_b32_e32 v2, 26, v2
	v_ashrrev_i32_e32 v3, 31, v1
	v_add_u32_e32 v2, v4, v2
	v_lshrrev_b32_e32 v3, 26, v3
	v_ashrrev_i32_e32 v10, 6, v2
	v_add_u32_e32 v3, v1, v3
	v_mul_i32_i24_e32 v2, 64, v10
	v_ashrrev_i32_e32 v9, 6, v3
	v_sub_u32_e32 v2, v4, v2
	v_lshlrev_b32_e32 v3, 5, v9
	v_ashrrev_i16_sdwa v2, v5, sext(v2) dst_sel:DWORD dst_unused:UNUSED_PAD src0_sel:DWORD src1_sel:BYTE_0
	v_and_b32_e32 v3, 32, v3
	v_bfe_i32 v11, v2, 0, 16
	v_add_u32_e32 v2, v3, v11
	v_lshlrev_b32_e32 v3, 3, v9
	v_and_b32_e32 v3, -16, v3
	v_add_u32_e32 v3, v10, v3
	v_lshlrev_b32_e32 v4, 7, v3
	v_lshl_add_u32 v134, v2, 1, v4
	s_add_u32 s1, s68, 0xa900000
	v_mad_u64_u32 v[136:137], s[2:3], v3, s4, v[134:135]
	s_addc_u32 s38, s69, 0
	s_lshr_b32 s2, s70, 30
	s_add_i32 s2, s70, s2
	s_ashr_i32 s22, s2, 2
	v_readlane_b32 s2, v252, 23
	s_sub_i32 s2, s2, s22
	s_lshl_b32 s2, s2, 2
	s_add_i32 s24, s2, s70
	s_ashr_i32 s8, s6, 6
	s_ashr_i32 s23, s22, 31
	s_ashr_i32 s25, s24, 31
	s_ashr_i32 s7, s6, 8
	s_lshl_b32 s39, s8, 10
	s_lshl_b64 s[2:3], s[22:23], 20
	s_lshl_b64 s[4:5], s[24:25], 20
	s_add_u32 s28, s1, s4
	s_addc_u32 s29, s38, s5
	s_add_i32 s25, s39, 0
	s_add_i32 m0, s25, 0x10000
	v_mov_b32_e32 v139, 0
	global_load_lds_dwordx4 v134, s[28:29]
	s_add_i32 m0, s25, 0x12000
	s_add_u32 s4, s28, 0x4000
	global_load_lds_dwordx4 v130, s[28:29]
	s_addc_u32 s5, s29, 0
	s_add_i32 m0, s25, 0x14000
	v_mov_b32_e32 v137, v139
	global_load_lds_dwordx4 v134, s[4:5]
	s_add_i32 m0, s25, 0x16000
	s_add_u32 s26, s76, s2
	s_addc_u32 s27, s33, s3
	s_add_i32 s40, s25, 0x2000
	global_load_lds_dwordx4 v130, s[4:5]
	s_mov_b32 m0, s25
	s_add_u32 s2, s26, 0x80000
	global_load_lds_dwordx4 v136, s[26:27]
	s_mov_b32 m0, s40
	s_addc_u32 s3, s27, 0
	s_add_i32 s41, s25, 0x4000
	global_load_lds_dwordx4 v132, s[26:27]
	s_mov_b32 m0, s41
	s_add_i32 s42, s25, 0x6000
	global_load_lds_dwordx4 v136, s[2:3]
	s_mov_b32 m0, s42
	v_mov_b32_e32 v133, v139
	global_load_lds_dwordx4 v132, s[2:3]
	s_cmp_eq_u32 s7, 1
	s_mov_b32 s43, 0
	v_mov_b32_e32 v135, v139
	v_mov_b32_e32 v131, v139
	s_mov_b64 s[4:5], 0x4000
	v_lshl_add_u64 v[2:3], s[26:27], 0, v[136:137]
	s_cselect_b64 s[2:3], -1, 0
	s_cmp_lg_u32 s7, 1
	v_lshl_add_u64 v[4:5], s[26:27], 0, v[132:133]
	s_cbranch_scc1 .LBB0_1836
	s_setprio 1
	s_barrier

; #define PG8_WAIT_V(n) asm volatile("s_waitcnt vmcnt(" #n ")" ::: "memory")
; #define PG8_BAR __builtin_amdgcn_s_barrier()
; template <class Epi, class Sched, bool ABLK = false, bool ALIGN_EPI = true, bool SP2 = true, bool BBLK = true>
; __device__ __forceinline__ void gemm_phase(LAS unsigned char* lds, const Gemm g, const Sched& S, const Epi& E) {
;     ...
;     PG8_WAIT_V(0);
;     if constexpr (!ALIGN_EPI) { if (wr == 0) PG8_BAR; }
;     PG8_BAR;
; __device__ __forceinline__ void xcd_barrier(const XcdBarrier& b) {
;     asm volatile("s_waitcnt vmcnt(0)" ::: "memory");
;     __syncthreads();
;     if (threadIdx.x == 0) {
;         unsigned* bar = b.bar;
;         __builtin_amdgcn_s_waitcnt(0);
;         unsigned nloc = b.st[0], nx = b.st[1];
;         if (nloc == 0u) { xcd_barrier_complete(bar, b.x, nloc, nx); b.st[0] = nloc; b.st[1] = nx; }
.LBB0_1849:
	s_waitcnt vmcnt(0)
	s_waitcnt vmcnt(0)
	s_setprio 0
	s_barrier
	s_and_saveexec_b64 s[2:3], s[92:93]
	s_cbranch_execz .LBB0_1901
	s_add_i32 s1, 0, 0x20000
	v_mov_b32_e32 v1, s1
	s_waitcnt vmcnt(0) expcnt(0) lgkmcnt(0)
	ds_read_b32 v3, v1
	s_add_i32 s1, 0, 0x20004
	v_mov_b32_e32 v1, s1
	ds_read_b32 v1, v1
	s_waitcnt lgkmcnt(1)
	v_cmp_ne_u32_e32 vcc, 0, v3
	s_cbranch_vccnz .LBB0_1865
	v_readlane_b32 s6, v252, 7
	v_readlane_b32 s7, v252, 8
	s_load_dwordx2 s[4:5], s[6:7], 0x4
	s_add_u32 s6, s68, 0x4200
	s_addc_u32 s7, s69, 0
	s_add_u32 s8, s68, 0x4400
	s_addc_u32 s9, s69, 0
	s_add_u32 s10, s68, 0x4500
	s_addc_u32 s11, s69, 0
	s_add_u32 s14, s68, 0x4600
	s_addc_u32 s15, s69, 0
	s_add_u32 s16, s68, 0x4700
	s_addc_u32 s17, s69, 0
	s_add_u32 s18, s68, 0x4800
	s_addc_u32 s19, s69, 0
	s_add_u32 s20, s68, 0x4900
	s_addc_u32 s21, s69, 0
	s_add_u32 s22, s68, 0x4a00
	s_addc_u32 s23, s69, 0
	s_add_u32 s24, s68, 0x4b00
	s_addc_u32 s25, s69, 0
	s_waitcnt lgkmcnt(0)
	s_mul_i32 s1, s4, s89
	s_add_u32 s4, s68, 0x4c00
	s_mul_i32 s1, s1, s5
	s_addc_u32 s5, s69, 0
	s_add_u32 s26, s68, 0x4d00
	s_addc_u32 s27, s69, 0
	s_add_u32 s28, s68, 0x4e00
	s_addc_u32 s29, s69, 0
	s_add_u32 s30, s68, 0x4f00
	s_addc_u32 s31, s69, 0
	s_add_u32 s34, s68, 0x5000
	s_addc_u32 s35, s69, 0
	s_add_u32 s36, s68, 0x5100
	s_addc_u32 s37, s69, 0
	s_add_u32 s38, s68, 0x5200
	s_addc_u32 s39, s69, 0
	s_add_u32 s40, s68, 0x5300
	s_addc_u32 s41, s69, 0
	s_mov_b32 s33, 1
	v_mov_b32_e32 v17, 0
	s_branch .LBB0_1853

; template <class Epi, class Sched, bool ABLK = false, bool ALIGN_EPI = true, bool SP2 = true, bool BBLK = true>
; __device__ __forceinline__ void gemm_phase(LAS unsigned char* lds, const Gemm g, const Sched& S, const Epi& E) {
;     const int tid = tid_fresh(), wid = __builtin_amdgcn_readfirstlane(tid >> 6), lane = tid & 63, wr = wid >> 2, wc = wid & 3, fr = lane & 15, fq = lane >> 4;
;     unsigned voffA[2], voffB[2];
; #pragma unroll
;     for (int i = 0; i < 2; ++i) { int R, C; stage_rc(tid * 16 + i * 8192, R, C); const int r32 = Epi::PERM ? perm32(R & 31) : (R & 31);
;         const int Rb = Epi::ADJ ? 64 * (R >> 5) + r32 : (R & ~31) + r32;
;         voffA[i] = (unsigned)(R * (ABLK ? 64 : g.lda) + C) * 2u; voffB[i] = BBLK ? (unsigned)(R * 64 + C) * 2u : (unsigned)(Rb * g.ldb + C) * 2u; }
;     const size_t kstep = (size_t)(BK * 2);
;     const size_t hstepA = (size_t)HALF * (ABLK ? 64 : g.lda) * 2, hstepB = BBLK ? (size_t)16384 : (size_t)(Epi::ADJ ? 32 : HALF) * g.ldb * 2;
;     const size_t tstepB = BBLK ? ((size_t)g.ldb / 64) * 32768 : (size_t)BM * g.ldb * 2;
;     const size_t kstepB = BBLK ? (size_t)32768 : kstep;
;     auto b_k0 = [&](int k0) -> size_t { return BBLK ? (size_t)(k0 / BK) * 32768 : (size_t)k0 * 2; };
;     const unsigned ldsw = (unsigned)wid * 1024u;
;     const int aoff = lds_byte(wr * 64 + fr, fq * 8), boff = lds_byte(wc * 32 + fr, fq * 8);
;     ...
;     Unit cur, nxt; int ui = 0;
;     if (!S.next(0, cur)) return;
;     f32x4 acc[2][2][4][2];
; #pragma unroll
;     for (int a = 0; a < 2; ++a)
; #pragma unroll
;         for (int b = 0; b < 2; ++b)
; #pragma unroll
;             for (int m = 0; m < 4; ++m)
; #pragma unroll
;                 for (int n = 0; n < 2; ++n) acc[a][b][m][n] = (f32x4){0.f, 0.f, 0.f, 0.f};
;     bf16x8 At[4][2], B0[2][2], B1[2][2];
;     auto a_unit = [&](const Unit& u) -> const char* { return ABLK ? (const char*)g.A + (size_t)u.pm * ((size_t)g.lda / 64) * 32768 : (const char*)g.A + (size_t)u.pm * 2 * hstepA; };
;     auto a_tile = [&](const char* ub, int tau) -> const char* { return ub + (size_t)tau * (ABLK ? (size_t)32768 : kstep); };
;     const char* uA = a_unit(cur); int tbA = cur.k0 / BK;
;     const char* cA = a_tile(uA, tbA); const char* cB = (const char*)g.Bt + (size_t)cur.pn * tstepB + b_k0(cur.k0);
;     S.a_ready(cur);
;     if constexpr (SP2) {
.LBB0_1901:
	s_or_b64 exec, exec, s[2:3]
	v_mov_b32_e32 v4, v0
	s_waitcnt lgkmcnt(0)
	s_barrier
	s_add_u32 s1, s68, 0x12900000
	v_bfe_i32 v3, v4, 27, 1
	v_lshlrev_b32_e32 v1, 4, v4
	v_lshrrev_b32_e32 v3, 22, v3
	v_add_u32_e32 v3, v1, v3
	v_and_b32_e32 v3, 0xfffffc00, v3
	v_sub_u32_e32 v3, v1, v3
	v_lshrrev_b32_e32 v5, 4, v3
	v_bitop3_b32 v5, v5, v3, 32 bitop3:0x6c
	v_ashrrev_i32_e32 v3, 31, v3
	v_lshrrev_b32_e32 v3, 26, v3
	v_ashrrev_i32_e32 v2, 31, v4
	v_add_u32_e32 v3, v5, v3
	v_lshrrev_b32_e32 v2, 26, v2
	v_ashrrev_i32_e32 v3, 6, v3
	v_add_u32_e32 v2, v4, v2
	v_mul_i32_i24_e32 v8, 64, v3
	v_ashrrev_i32_e32 v2, 6, v2
	v_sub_u32_e32 v5, v5, v8
	v_mov_b32_e32 v8, 1
	v_lshlrev_b32_e32 v6, 3, v2
	v_lshlrev_b32_e32 v7, 5, v2
	v_ashrrev_i16_sdwa v5, v8, sext(v5) dst_sel:DWORD dst_unused:UNUSED_PAD src0_sel:DWORD src1_sel:BYTE_0
	v_and_b32_e32 v6, 0x1fffff0, v6
	v_and_b32_e32 v7, 32, v7
	v_bfe_i32 v5, v5, 0, 16
	v_add_u32_e32 v7, v7, v5
	v_add_lshl_u32 v6, v3, v6, 7
	v_add_u32_e32 v1, 0x2000, v1
	v_lshl_add_u32 v130, v7, 1, v6
	v_ashrrev_i32_e32 v6, 31, v1
	v_lshrrev_b32_e32 v6, 22, v6
	v_add_u32_e32 v6, v1, v6
	v_ashrrev_i32_e32 v6, 10, v6
	v_mul_i32_i24_e32 v7, 0x400, v6
	v_sub_u32_e32 v1, v1, v7
	v_lshrrev_b32_e32 v7, 4, v1
	v_bitop3_b32 v1, v7, v1, 32 bitop3:0x6c
	v_lshlrev_b32_e32 v7, 3, v6
	v_and_b32_e32 v9, 0x1fffff0, v7
	v_ashrrev_i32_e32 v7, 31, v1
	v_readfirstlane_b32 s4, v4
	v_lshrrev_b32_e32 v7, 26, v7
	s_addc_u32 s33, s69, 0
	s_ashr_i32 s5, s4, 6
	v_add_u32_e32 v10, v1, v7
	v_ashrrev_i32_e32 v7, 6, v10
	v_and_b32_e32 v10, 0xc0, v10
	s_ashr_i32 s6, s4, 8
	s_lshl_b32 s40, s5, 10
	v_readlane_b32 s2, v252, 16
	v_sub_u32_e32 v1, v1, v10
	s_add_u32 s30, s1, s2
	v_lshlrev_b32_e32 v11, 5, v6
	v_ashrrev_i16_sdwa v1, v8, sext(v1) dst_sel:DWORD dst_unused:UNUSED_PAD src0_sel:DWORD src1_sel:BYTE_0
	s_addc_u32 s31, s33, 0
	s_add_i32 s41, s40, 0
	v_and_b32_e32 v11, 32, v11
	v_bfe_i32 v8, v1, 0, 16
	s_add_i32 m0, s41, 0x10000
	v_add_u32_e32 v1, v11, v8
	v_add_lshl_u32 v9, v7, v9, 7
	global_load_lds_dwordx4 v130, s[30:31]
	s_add_i32 m0, s41, 0x12000
	v_lshl_add_u32 v132, v1, 1, v9
	s_add_u32 s2, s30, 0x4000
	global_load_lds_dwordx4 v132, s[30:31]
	s_addc_u32 s3, s31, 0
	s_add_i32 m0, s41, 0x14000
	v_mov_b32_e32 v131, 0
	global_load_lds_dwordx4 v130, s[2:3]
	s_add_i32 m0, s41, 0x16000
	s_mov_b32 s47, 0
	global_load_lds_dwordx4 v132, s[2:3]
	v_readlane_b32 s2, v252, 17
	v_readlane_b32 s3, v252, 18
	s_add_u32 s34, s62, s2
	s_addc_u32 s35, s83, s3
	s_add_i32 s42, s41, 0x2000
	s_mov_b32 m0, s41
	s_add_u32 s2, s34, 0x4000
	global_load_lds_dwordx4 v130, s[34:35]
	s_mov_b32 m0, s42
	s_addc_u32 s3, s35, 0
	s_add_i32 s43, s41, 0x4000
	global_load_lds_dwordx4 v132, s[34:35]
	s_mov_b32 m0, s43
	s_add_i32 s44, s41, 0x6000
	global_load_lds_dwordx4 v130, s[2:3]
	s_mov_b32 m0, s44
	s_cmp_eq_u32 s6, 1
	global_load_lds_dwordx4 v132, s[2:3]
	s_cselect_b64 s[2:3], -1, 0
	s_cmp_lg_u32 s6, 1
	v_mov_b32_e32 v133, v131
	s_cbranch_scc1 .LBB0_1903
	s_setprio 1
	s_barrier

; #define PG8_WAIT_V(n) asm volatile("s_waitcnt vmcnt(" #n ")" ::: "memory")
; #define PG8_BAR __builtin_amdgcn_s_barrier()
; template <class Epi, class Sched, bool ABLK = false, bool ALIGN_EPI = true, bool SP2 = true, bool BBLK = true>
; __device__ __forceinline__ void gemm_phase(LAS unsigned char* lds, const Gemm g, const Sched& S, const Epi& E) {
;     ...
;     PG8_WAIT_V(0);
;     if constexpr (!ALIGN_EPI) { if (wr == 0) PG8_BAR; }
;     PG8_BAR;
; __device__ __forceinline__ void xcd_barrier(const XcdBarrier& b) {
;     asm volatile("s_waitcnt vmcnt(0)" ::: "memory");
;     __syncthreads();
;     if (threadIdx.x == 0) {
;         unsigned* bar = b.bar;
;         __builtin_amdgcn_s_waitcnt(0);
;         unsigned nloc = b.st[0], nx = b.st[1];
;         if (nloc == 0u) { xcd_barrier_complete(bar, b.x, nloc, nx); b.st[0] = nloc; b.st[1] = nx; }
.LBB0_1913:
	s_waitcnt vmcnt(0)
	s_barrier
	s_waitcnt vmcnt(0)
	s_waitcnt vmcnt(0)
	s_setprio 0
	s_barrier
	s_and_saveexec_b64 s[2:3], s[92:93]
	v_readlane_b32 s56, v252, 10
	v_readlane_b32 s63, v252, 23
	v_readlane_b32 s57, v252, 11
	s_cbranch_execz .LBB0_1965
	s_add_i32 s1, 0, 0x20000
	v_mov_b32_e32 v1, s1
	s_waitcnt vmcnt(0) expcnt(0) lgkmcnt(0)
	ds_read_b32 v3, v1
	s_add_i32 s1, 0, 0x20004
	v_mov_b32_e32 v1, s1
	ds_read_b32 v1, v1
	s_waitcnt lgkmcnt(1)
	v_cmp_ne_u32_e32 vcc, 0, v3
	s_cbranch_vccnz .LBB0_1929
	v_readlane_b32 s6, v252, 7
	v_readlane_b32 s7, v252, 8
	s_load_dwordx2 s[4:5], s[6:7], 0x4
	s_add_u32 s6, s68, 0x4200
	s_addc_u32 s7, s69, 0
	s_add_u32 s8, s68, 0x4400
	s_addc_u32 s9, s69, 0
	s_add_u32 s10, s68, 0x4500
	s_addc_u32 s11, s69, 0
	s_add_u32 s12, s68, 0x4600
	s_addc_u32 s13, s69, 0
	s_add_u32 s14, s68, 0x4700
	s_addc_u32 s15, s69, 0
	s_add_u32 s16, s68, 0x4800
	s_addc_u32 s17, s69, 0
	s_add_u32 s18, s68, 0x4900
	s_addc_u32 s19, s69, 0
	s_add_u32 s20, s68, 0x4a00
	s_addc_u32 s21, s69, 0
	s_add_u32 s22, s68, 0x4b00
	s_addc_u32 s23, s69, 0
	s_waitcnt lgkmcnt(0)
	s_mul_i32 s1, s4, s89
	s_add_u32 s4, s68, 0x4c00
	s_mul_i32 s1, s1, s5
	s_addc_u32 s5, s69, 0
	s_add_u32 s24, s68, 0x4d00
	s_addc_u32 s25, s69, 0
	s_add_u32 s26, s68, 0x4e00
	s_addc_u32 s27, s69, 0
	s_add_u32 s28, s68, 0x4f00
	s_addc_u32 s29, s69, 0
	s_add_u32 s30, s68, 0x5000
	s_addc_u32 s31, s69, 0
	s_add_u32 s34, s68, 0x5100
	s_addc_u32 s35, s69, 0
	s_add_u32 s36, s68, 0x5200
	s_addc_u32 s37, s69, 0
	s_add_u32 s38, s68, 0x5300
	s_addc_u32 s39, s69, 0
	s_mov_b32 s33, 1
	v_mov_b32_e32 v17, 0
	s_branch .LBB0_1917

; template <class Epi, class Sched, bool ABLK = false, bool ALIGN_EPI = true, bool SP2 = true, bool BBLK = true>
; __device__ __forceinline__ void gemm_phase(LAS unsigned char* lds, const Gemm g, const Sched& S, const Epi& E) {
;     const int tid = tid_fresh(), wid = __builtin_amdgcn_readfirstlane(tid >> 6), lane = tid & 63, wr = wid >> 2, wc = wid & 3, fr = lane & 15, fq = lane >> 4;
;     unsigned voffA[2], voffB[2];
; #pragma unroll
;     for (int i = 0; i < 2; ++i) { int R, C; stage_rc(tid * 16 + i * 8192, R, C); const int r32 = Epi::PERM ? perm32(R & 31) : (R & 31);
;         const int Rb = Epi::ADJ ? 64 * (R >> 5) + r32 : (R & ~31) + r32;
;         voffA[i] = (unsigned)(R * (ABLK ? 64 : g.lda) + C) * 2u; voffB[i] = BBLK ? (unsigned)(R * 64 + C) * 2u : (unsigned)(Rb * g.ldb + C) * 2u; }
;     const size_t kstep = (size_t)(BK * 2);
;     const size_t hstepA = (size_t)HALF * (ABLK ? 64 : g.lda) * 2, hstepB = BBLK ? (size_t)16384 : (size_t)(Epi::ADJ ? 32 : HALF) * g.ldb * 2;
;     const size_t tstepB = BBLK ? ((size_t)g.ldb / 64) * 32768 : (size_t)BM * g.ldb * 2;
;     const size_t kstepB = BBLK ? (size_t)32768 : kstep;
;     auto b_k0 = [&](int k0) -> size_t { return BBLK ? (size_t)(k0 / BK) * 32768 : (size_t)k0 * 2; };
;     const unsigned ldsw = (unsigned)wid * 1024u;
;     const int aoff = lds_byte(wr * 64 + fr, fq * 8), boff = lds_byte(wc * 32 + fr, fq * 8);
;     ...
;     Unit cur, nxt; int ui = 0;
;     if (!S.next(0, cur)) return;
;     f32x4 acc[2][2][4][2];
; #pragma unroll
;     for (int a = 0; a < 2; ++a)
; #pragma unroll
;         for (int b = 0; b < 2; ++b)
; #pragma unroll
;             for (int m = 0; m < 4; ++m)
; #pragma unroll
;                 for (int n = 0; n < 2; ++n) acc[a][b][m][n] = (f32x4){0.f, 0.f, 0.f, 0.f};
;     bf16x8 At[4][2], B0[2][2], B1[2][2];
;     auto a_unit = [&](const Unit& u) -> const char* { return ABLK ? (const char*)g.A + (size_t)u.pm * ((size_t)g.lda / 64) * 32768 : (const char*)g.A + (size_t)u.pm * 2 * hstepA; };
;     auto a_tile = [&](const char* ub, int tau) -> const char* { return ub + (size_t)tau * (ABLK ? (size_t)32768 : kstep); };
;     const char* uA = a_unit(cur); int tbA = cur.k0 / BK;
;     const char* cA = a_tile(uA, tbA); const char* cB = (const char*)g.Bt + (size_t)cur.pn * tstepB + b_k0(cur.k0);
;     S.a_ready(cur);
;     if constexpr (SP2) {
.LBB0_2129:
	s_or_b64 exec, exec, s[2:3]
	v_readlane_b32 s2, v252, 12
	s_add_u32 s8, s68, 0x1e100000
	v_mov_b32_e32 v6, v0
	v_readlane_b32 s3, v252, 13
	s_addc_u32 s9, s69, 0
	s_waitcnt lgkmcnt(0)
	s_barrier
	s_andn2_b64 vcc, exec, s[2:3]
	v_readfirstlane_b32 s4, v6
	s_cbranch_vccnz .LBB0_2145
	v_lshlrev_b32_e32 v1, 4, v6
	v_add_u32_e32 v2, 0x2000, v1
	v_ashrrev_i32_e32 v3, 31, v2
	v_lshrrev_b32_e32 v3, 22, v3
	v_add_u32_e32 v3, v2, v3
	v_ashrrev_i32_e32 v7, 10, v3
	v_mul_i32_i24_e32 v4, 0x400, v7
	v_sub_u32_e32 v2, v2, v4
	v_lshrrev_b32_e32 v4, 4, v2
	v_bitop3_b32 v2, v4, v2, 32 bitop3:0x6c
	v_ashrrev_i32_e32 v4, 31, v2
	v_lshrrev_b32_e32 v4, 26, v4
	v_add_u32_e32 v4, v2, v4
	v_ashrrev_i32_e32 v8, 6, v4
	v_and_b32_e32 v4, 0xc0, v4
	v_sub_u32_e32 v2, v2, v4
	v_mov_b32_e32 v4, 1
	v_lshlrev_b32_e32 v3, 5, v7
	v_ashrrev_i16_sdwa v2, v4, sext(v2) dst_sel:DWORD dst_unused:UNUSED_PAD src0_sel:DWORD src1_sel:BYTE_0
	v_and_b32_e32 v3, 32, v3
	v_bfe_i32 v9, v2, 0, 16
	v_add_u32_e32 v2, v3, v9
	v_lshlrev_b32_e32 v3, 3, v7
	v_and_b32_e32 v3, -16, v3
	v_add_u32_e32 v3, v8, v3
	v_lshlrev_b32_e32 v5, 7, v3
	v_lshl_add_u32 v130, v2, 1, v5
	s_movk_i32 s7, 0xf80
	v_mad_u64_u32 v[132:133], s[2:3], v3, s7, v[130:131]
	v_bfe_i32 v3, v6, 27, 1
	v_lshrrev_b32_e32 v3, 22, v3
	v_add_u32_e32 v3, v1, v3
	v_and_b32_e32 v3, 0xfffffc00, v3
	v_sub_u32_e32 v1, v1, v3
	v_lshrrev_b32_e32 v3, 4, v1
	v_bitop3_b32 v3, v3, v1, 32 bitop3:0x6c
	v_ashrrev_i32_e32 v1, 31, v1
	v_lshrrev_b32_e32 v1, 26, v1
	v_ashrrev_i32_e32 v2, 31, v6
	v_add_u32_e32 v1, v3, v1
	v_lshrrev_b32_e32 v2, 26, v2
	v_ashrrev_i32_e32 v11, 6, v1
	v_add_u32_e32 v2, v6, v2
	v_mul_i32_i24_e32 v1, 64, v11
	v_ashrrev_i32_e32 v10, 6, v2
	v_sub_u32_e32 v1, v3, v1
	v_lshlrev_b32_e32 v2, 5, v10
	v_ashrrev_i16_sdwa v1, v4, sext(v1) dst_sel:DWORD dst_unused:UNUSED_PAD src0_sel:DWORD src1_sel:BYTE_0
	v_and_b32_e32 v2, 32, v2
	v_bfe_i32 v12, v1, 0, 16
	v_add_u32_e32 v1, v2, v12
	v_lshlrev_b32_e32 v2, 3, v10
	v_and_b32_e32 v2, -16, v2
	s_add_u32 s1, s68, 0x1100000
	v_add_u32_e32 v2, v11, v2
	s_addc_u32 s33, s69, 0
	s_ashr_i32 s6, s4, 6
	v_lshlrev_b32_e32 v3, 7, v2
	s_ashr_i32 s5, s4, 8
	s_lshl_b32 s36, s6, 10
	v_lshl_add_u32 v134, v1, 1, v3
	s_add_u32 s37, s68, 0x2d100000
	v_mad_u64_u32 v[136:137], s[2:3], v2, s7, v[134:135]
	s_addc_u32 s38, s69, 0
	s_lshr_b32 s2, s70, 31
	s_add_i32 s2, s70, s2
	s_ashr_i32 s20, s2, 1
	s_sub_i32 s2, s63, s20
	s_lshl_b32 s2, s2, 1
	s_add_i32 s22, s2, s70
	s_ashr_i32 s21, s20, 31
	s_ashr_i32 s23, s22, 31
	s_lshl_b64 s[2:3], s[20:21], 20
	s_lshl_b64 s[10:11], s[22:23], 20
	s_add_u32 s26, s1, s10
	s_addc_u32 s27, s33, s11
	s_add_i32 s21, s36, 0
	s_add_i32 m0, s21, 0x10000
	v_mov_b32_e32 v135, 0
	global_load_lds_dwordx4 v134, s[26:27]
	s_add_i32 m0, s21, 0x12000
	s_add_u32 s10, s26, 0x4000
	global_load_lds_dwordx4 v130, s[26:27]
	s_addc_u32 s11, s27, 0
	s_add_i32 m0, s21, 0x14000
	v_mov_b32_e32 v137, v135
	global_load_lds_dwordx4 v134, s[10:11]
	s_add_i32 m0, s21, 0x16000
	s_add_u32 s24, s37, s2
	s_addc_u32 s25, s38, s3
	s_add_i32 s23, s21, 0x2000
	global_load_lds_dwordx4 v130, s[10:11]
	s_mov_b32 m0, s21
	s_add_u32 s2, s24, 0x80000
	global_load_lds_dwordx4 v136, s[24:25]
	s_mov_b32 m0, s23
	s_addc_u32 s3, s25, 0
	s_add_i32 s39, s21, 0x4000
	global_load_lds_dwordx4 v132, s[24:25]
	s_mov_b32 m0, s39
	s_add_i32 s40, s21, 0x6000
	global_load_lds_dwordx4 v136, s[2:3]
	s_mov_b32 m0, s40
	v_mov_b32_e32 v133, v135
	global_load_lds_dwordx4 v132, s[2:3]
	s_cmp_eq_u32 s5, 1
	s_mov_b32 s41, 0
	v_mov_b32_e32 v131, v135
	v_lshl_add_u64 v[2:3], s[24:25], 0, v[136:137]
	s_cselect_b64 s[2:3], -1, 0
	s_cmp_lg_u32 s5, 1
	v_lshl_add_u64 v[4:5], s[24:25], 0, v[132:133]
	s_cbranch_scc1 .LBB0_2132
	s_setprio 1
	s_barrier

; #define PG8_WAIT_V(n) asm volatile("s_waitcnt vmcnt(" #n ")" ::: "memory")
; #define PG8_BAR __builtin_amdgcn_s_barrier()
; template <class Epi, class Sched, bool ABLK = false, bool ALIGN_EPI = true, bool SP2 = true, bool BBLK = true>
; __device__ __forceinline__ void gemm_phase(LAS unsigned char* lds, const Gemm g, const Sched& S, const Epi& E) {
;     ...
;     PG8_WAIT_V(0);
;     if constexpr (!ALIGN_EPI) { if (wr == 0) PG8_BAR; }
;     PG8_BAR;
; __device__ __forceinline__ void xcd_barrier(const XcdBarrier& b) {
;     asm volatile("s_waitcnt vmcnt(0)" ::: "memory");
;     __syncthreads();
;     if (threadIdx.x == 0) {
;         unsigned* bar = b.bar;
;         __builtin_amdgcn_s_waitcnt(0);
;         unsigned nloc = b.st[0], nx = b.st[1];
;         if (nloc == 0u) { xcd_barrier_complete(bar, b.x, nloc, nx); b.st[0] = nloc; b.st[1] = nx; }
.LBB0_2145:
	s_waitcnt vmcnt(0)
	s_waitcnt vmcnt(0)
	s_setprio 0
	s_barrier
	s_and_saveexec_b64 s[2:3], s[92:93]
	s_cbranch_execz .LBB0_2197
	s_add_i32 s1, 0, 0x20000
	v_mov_b32_e32 v1, s1
	s_waitcnt vmcnt(0) expcnt(0) lgkmcnt(0)
	ds_read_b32 v3, v1
	s_add_i32 s1, 0, 0x20004
	v_mov_b32_e32 v1, s1
	ds_read_b32 v1, v1
	s_waitcnt lgkmcnt(1)
	v_cmp_ne_u32_e32 vcc, 0, v3
	s_cbranch_vccnz .LBB0_2161
	v_readlane_b32 s6, v252, 7
	v_readlane_b32 s7, v252, 8
	s_load_dwordx2 s[4:5], s[6:7], 0x4
	s_add_u32 s6, s68, 0x4200
	s_addc_u32 s7, s69, 0
	s_add_u32 s10, s68, 0x4400
	s_addc_u32 s11, s69, 0
	s_add_u32 s12, s68, 0x4500
	s_addc_u32 s13, s69, 0
	s_add_u32 s14, s68, 0x4600
	s_addc_u32 s15, s69, 0
	s_add_u32 s16, s68, 0x4700
	s_addc_u32 s17, s69, 0
	s_add_u32 s18, s68, 0x4800
	s_addc_u32 s19, s69, 0
	s_add_u32 s20, s68, 0x4900
	s_addc_u32 s21, s69, 0
	s_add_u32 s22, s68, 0x4a00
	s_addc_u32 s23, s69, 0
	s_add_u32 s24, s68, 0x4b00
	s_addc_u32 s25, s69, 0
	s_waitcnt lgkmcnt(0)
	s_mul_i32 s1, s4, s89
	s_add_u32 s4, s68, 0x4c00
	s_mul_i32 s1, s1, s5
	s_addc_u32 s5, s69, 0
	s_add_u32 s26, s68, 0x4d00
	s_addc_u32 s27, s69, 0
	s_add_u32 s28, s68, 0x4e00
	s_addc_u32 s29, s69, 0
	s_add_u32 s30, s68, 0x4f00
	s_addc_u32 s31, s69, 0
	s_add_u32 s34, s68, 0x5000
	s_addc_u32 s35, s69, 0
	s_add_u32 s36, s68, 0x5100
	s_addc_u32 s37, s69, 0
	s_add_u32 s38, s68, 0x5200
	s_addc_u32 s39, s69, 0
	s_add_u32 s40, s68, 0x5300
	s_addc_u32 s41, s69, 0
	s_mov_b32 s33, 1
	v_mov_b32_e32 v17, 0
	s_branch .LBB0_2149

; template <class Epi, class Sched, bool ABLK = false, bool ALIGN_EPI = true, bool SP2 = true, bool BBLK = true>
; __device__ __forceinline__ void gemm_phase(LAS unsigned char* lds, const Gemm g, const Sched& S, const Epi& E) {
;     const int tid = tid_fresh(), wid = __builtin_amdgcn_readfirstlane(tid >> 6), lane = tid & 63, wr = wid >> 2, wc = wid & 3, fr = lane & 15, fq = lane >> 4;
;     unsigned voffA[2], voffB[2];
; #pragma unroll
;     for (int i = 0; i < 2; ++i) { int R, C; stage_rc(tid * 16 + i * 8192, R, C); const int r32 = Epi::PERM ? perm32(R & 31) : (R & 31);
;         const int Rb = Epi::ADJ ? 64 * (R >> 5) + r32 : (R & ~31) + r32;
;         voffA[i] = (unsigned)(R * (ABLK ? 64 : g.lda) + C) * 2u; voffB[i] = BBLK ? (unsigned)(R * 64 + C) * 2u : (unsigned)(Rb * g.ldb + C) * 2u; }
;     const size_t kstep = (size_t)(BK * 2);
;     const size_t hstepA = (size_t)HALF * (ABLK ? 64 : g.lda) * 2, hstepB = BBLK ? (size_t)16384 : (size_t)(Epi::ADJ ? 32 : HALF) * g.ldb * 2;
;     const size_t tstepB = BBLK ? ((size_t)g.ldb / 64) * 32768 : (size_t)BM * g.ldb * 2;
;     const size_t kstepB = BBLK ? (size_t)32768 : kstep;
;     auto b_k0 = [&](int k0) -> size_t { return BBLK ? (size_t)(k0 / BK) * 32768 : (size_t)k0 * 2; };
;     const unsigned ldsw = (unsigned)wid * 1024u;
;     const int aoff = lds_byte(wr * 64 + fr, fq * 8), boff = lds_byte(wc * 32 + fr, fq * 8);
;     ...
;     Unit cur, nxt; int ui = 0;
;     if (!S.next(0, cur)) return;
;     f32x4 acc[2][2][4][2];
; #pragma unroll
;     for (int a = 0; a < 2; ++a)
; #pragma unroll
;         for (int b = 0; b < 2; ++b)
; #pragma unroll
;             for (int m = 0; m < 4; ++m)
; #pragma unroll
;                 for (int n = 0; n < 2; ++n) acc[a][b][m][n] = (f32x4){0.f, 0.f, 0.f, 0.f};
;     bf16x8 At[4][2], B0[2][2], B1[2][2];
;     auto a_unit = [&](const Unit& u) -> const char* { return ABLK ? (const char*)g.A + (size_t)u.pm * ((size_t)g.lda / 64) * 32768 : (const char*)g.A + (size_t)u.pm * 2 * hstepA; };
;     auto a_tile = [&](const char* ub, int tau) -> const char* { return ub + (size_t)tau * (ABLK ? (size_t)32768 : kstep); };
;     const char* uA = a_unit(cur); int tbA = cur.k0 / BK;
;     const char* cA = a_tile(uA, tbA); const char* cB = (const char*)g.Bt + (size_t)cur.pn * tstepB + b_k0(cur.k0);
;     S.a_ready(cur);
;     if constexpr (SP2) {
.LBB0_2254:
	s_or_b64 exec, exec, s[2:3]
	v_readlane_b32 s2, v252, 26
	s_add_u32 s1, s68, 0x23100000
	s_waitcnt lgkmcnt(0)
	v_mov_b32_e32 v1, v0
	v_readlane_b32 s3, v252, 27
	s_addc_u32 s33, s69, 0
	s_barrier
	s_and_b64 vcc, exec, s[2:3]
	v_readfirstlane_b32 s2, v1
	s_cbranch_vccnz .LBB0_2270
	v_lshlrev_b32_e32 v2, 4, v1
	v_add_u32_e32 v3, 0x2000, v2
	v_ashrrev_i32_e32 v4, 31, v3
	v_lshrrev_b32_e32 v4, 22, v4
	v_add_u32_e32 v4, v3, v4
	v_ashrrev_i32_e32 v6, 10, v4
	v_mul_i32_i24_e32 v5, 0x400, v6
	v_sub_u32_e32 v3, v3, v5
	v_lshrrev_b32_e32 v5, 4, v3
	v_bitop3_b32 v3, v5, v3, 32 bitop3:0x6c
	v_ashrrev_i32_e32 v5, 31, v3
	v_lshrrev_b32_e32 v5, 26, v5
	v_add_u32_e32 v5, v3, v5
	v_ashrrev_i32_e32 v7, 6, v5
	v_and_b32_e32 v5, 0xc0, v5
	v_sub_u32_e32 v3, v3, v5
	v_mov_b32_e32 v5, 1
	v_lshlrev_b32_e32 v4, 5, v6
	v_ashrrev_i16_sdwa v3, v5, sext(v3) dst_sel:DWORD dst_unused:UNUSED_PAD src0_sel:DWORD src1_sel:BYTE_0
	v_and_b32_e32 v4, 32, v4
	v_bfe_i32 v8, v3, 0, 16
	v_add_u32_e32 v3, v4, v8
	v_lshlrev_b32_e32 v4, 3, v6
	v_and_b32_e32 v4, -16, v4
	v_add_u32_e32 v4, v7, v4
	v_lshlrev_b32_e32 v9, 7, v4
	v_lshl_add_u32 v130, v3, 1, v9
	s_movk_i32 s6, 0xf80
	v_mad_u64_u32 v[132:133], s[4:5], v4, s6, v[130:131]
	v_bfe_i32 v4, v1, 27, 1
	v_lshrrev_b32_e32 v4, 22, v4
	v_add_u32_e32 v4, v2, v4
	v_and_b32_e32 v4, 0xfffffc00, v4
	v_sub_u32_e32 v2, v2, v4
	v_lshrrev_b32_e32 v4, 4, v2
	v_bitop3_b32 v4, v4, v2, 32 bitop3:0x6c
	v_ashrrev_i32_e32 v2, 31, v2
	v_lshrrev_b32_e32 v2, 26, v2
	v_ashrrev_i32_e32 v3, 31, v1
	v_add_u32_e32 v2, v4, v2
	v_lshrrev_b32_e32 v3, 26, v3
	v_ashrrev_i32_e32 v10, 6, v2
	v_add_u32_e32 v3, v1, v3
	v_mul_i32_i24_e32 v2, 64, v10
	v_ashrrev_i32_e32 v9, 6, v3
	v_sub_u32_e32 v2, v4, v2
	v_lshlrev_b32_e32 v3, 5, v9
	v_ashrrev_i16_sdwa v2, v5, sext(v2) dst_sel:DWORD dst_unused:UNUSED_PAD src0_sel:DWORD src1_sel:BYTE_0
	v_and_b32_e32 v3, 32, v3
	v_bfe_i32 v11, v2, 0, 16
	v_add_u32_e32 v2, v3, v11
	v_lshlrev_b32_e32 v3, 3, v9
	v_and_b32_e32 v3, -16, v3
	s_add_u32 s38, s68, 0xc900000
	v_add_u32_e32 v3, v10, v3
	s_addc_u32 s39, s69, 0
	s_ashr_i32 s10, s2, 6
	v_lshlrev_b32_e32 v4, 7, v3
	s_ashr_i32 s3, s2, 8
	s_lshl_b32 s40, s10, 10
	v_lshl_add_u32 v134, v2, 1, v4
	s_add_u32 s41, s68, 0x1b900000
	v_mad_u64_u32 v[136:137], s[4:5], v3, s6, v[134:135]
	s_addc_u32 s42, s69, 0
	s_lshr_b32 s4, s70, 30
	s_add_i32 s4, s70, s4
	s_ashr_i32 s22, s4, 2
	s_sub_i32 s4, s63, s22
	s_lshl_b32 s4, s4, 2
	s_add_i32 s24, s4, s70
	s_ashr_i32 s23, s22, 31
	s_ashr_i32 s25, s24, 31
	s_lshl_b64 s[4:5], s[22:23], 20
	s_lshl_b64 s[6:7], s[24:25], 20
	s_add_u32 s28, s38, s6
	s_addc_u32 s29, s39, s7
	s_add_i32 s25, s40, 0
	s_add_i32 m0, s25, 0x10000
	v_mov_b32_e32 v139, 0
	global_load_lds_dwordx4 v134, s[28:29]
	s_add_i32 m0, s25, 0x12000
	s_add_u32 s6, s28, 0x4000
	global_load_lds_dwordx4 v130, s[28:29]
	s_addc_u32 s7, s29, 0
	s_add_i32 m0, s25, 0x14000
	v_mov_b32_e32 v137, v139
	global_load_lds_dwordx4 v134, s[6:7]
	s_add_i32 m0, s25, 0x16000
	s_add_u32 s26, s41, s4
	s_addc_u32 s27, s42, s5
	s_add_i32 s43, s25, 0x2000
	global_load_lds_dwordx4 v130, s[6:7]
	s_mov_b32 m0, s25
	s_add_u32 s4, s26, 0x80000
	global_load_lds_dwordx4 v136, s[26:27]
	s_mov_b32 m0, s43
	s_addc_u32 s5, s27, 0
	s_add_i32 s44, s25, 0x4000
	global_load_lds_dwordx4 v132, s[26:27]
	s_mov_b32 m0, s44
	s_add_i32 s45, s25, 0x6000
	global_load_lds_dwordx4 v136, s[4:5]
	s_mov_b32 m0, s45
	v_mov_b32_e32 v133, v139
	global_load_lds_dwordx4 v132, s[4:5]
	s_cmp_eq_u32 s3, 1
	s_mov_b32 s46, 0
	v_mov_b32_e32 v135, v139
	v_mov_b32_e32 v131, v139
	s_mov_b64 s[4:5], 0x4000
	v_lshl_add_u64 v[2:3], s[26:27], 0, v[136:137]
	s_cselect_b64 s[6:7], -1, 0
	s_cmp_lg_u32 s3, 1
	v_lshl_add_u64 v[4:5], s[26:27], 0, v[132:133]
	s_cbranch_scc1 .LBB0_2257
	s_setprio 1
	s_barrier

; #define PG8_WAIT_V(n) asm volatile("s_waitcnt vmcnt(" #n ")" ::: "memory")
; #define PG8_BAR __builtin_amdgcn_s_barrier()
; template <class Epi, class Sched, bool ABLK = false, bool ALIGN_EPI = true, bool SP2 = true, bool BBLK = true>
; __device__ __forceinline__ void gemm_phase(LAS unsigned char* lds, const Gemm g, const Sched& S, const Epi& E) {
;     ...
;     PG8_WAIT_V(0);
;     if constexpr (!ALIGN_EPI) { if (wr == 0) PG8_BAR; }
;     PG8_BAR;
; __device__ __forceinline__ void xcd_barrier(const XcdBarrier& b) {
;     asm volatile("s_waitcnt vmcnt(0)" ::: "memory");
;     __syncthreads();
;     if (threadIdx.x == 0) {
;         unsigned* bar = b.bar;
;         __builtin_amdgcn_s_waitcnt(0);
;         unsigned nloc = b.st[0], nx = b.st[1];
;         if (nloc == 0u) { xcd_barrier_complete(bar, b.x, nloc, nx); b.st[0] = nloc; b.st[1] = nx; }
.LBB0_2270:
	s_waitcnt vmcnt(0)
	s_waitcnt vmcnt(0)
	s_setprio 0
	s_barrier
	s_and_saveexec_b64 s[2:3], s[92:93]
	s_cbranch_execz .LBB0_2322
	s_add_i32 s4, 0, 0x20000
	v_mov_b32_e32 v1, s4
	s_waitcnt vmcnt(0) expcnt(0) lgkmcnt(0)
	ds_read_b32 v3, v1
	s_add_i32 s4, 0, 0x20004
	v_mov_b32_e32 v1, s4
	ds_read_b32 v1, v1
	s_waitcnt lgkmcnt(1)
	v_cmp_ne_u32_e32 vcc, 0, v3
	s_cbranch_vccnz .LBB0_2286
	v_readlane_b32 s6, v252, 7
	v_readlane_b32 s7, v252, 8
	s_load_dwordx2 s[4:5], s[6:7], 0x4
	s_add_u32 s6, s68, 0x4200
	s_addc_u32 s7, s69, 0
	s_add_u32 s10, s68, 0x4400
	s_addc_u32 s11, s69, 0
	s_add_u32 s12, s68, 0x4500
	s_addc_u32 s13, s69, 0
	s_add_u32 s14, s68, 0x4600
	s_addc_u32 s15, s69, 0
	s_add_u32 s16, s68, 0x4700
	s_addc_u32 s17, s69, 0
	s_add_u32 s18, s68, 0x4800
	s_addc_u32 s19, s69, 0
	s_add_u32 s20, s68, 0x4900
	s_addc_u32 s21, s69, 0
	s_add_u32 s22, s68, 0x4a00
	s_addc_u32 s23, s69, 0
	s_add_u32 s24, s68, 0x4b00
	s_addc_u32 s25, s69, 0
	s_waitcnt lgkmcnt(0)
	s_mul_i32 s48, s4, s89
	s_add_u32 s4, s68, 0x4c00
	s_mul_i32 s48, s48, s5
	s_addc_u32 s5, s69, 0
	s_add_u32 s26, s68, 0x4d00
	s_addc_u32 s27, s69, 0
	s_add_u32 s28, s68, 0x4e00
	s_addc_u32 s29, s69, 0
	s_add_u32 s30, s68, 0x4f00
	s_addc_u32 s31, s69, 0
	s_add_u32 s34, s68, 0x5000
	s_addc_u32 s35, s69, 0
	s_add_u32 s36, s68, 0x5100
	s_addc_u32 s37, s69, 0
	s_add_u32 s38, s68, 0x5200
	s_addc_u32 s39, s69, 0
	s_add_u32 s40, s68, 0x5300
	s_addc_u32 s41, s69, 0
	s_mov_b32 s49, 1
	v_mov_b32_e32 v17, 0
	s_branch .LBB0_2274

; template <class Epi, class Sched, bool ABLK = false, bool ALIGN_EPI = true, bool SP2 = true, bool BBLK = true>
; __device__ __forceinline__ void gemm_phase(LAS unsigned char* lds, const Gemm g, const Sched& S, const Epi& E) {
;     const int tid = tid_fresh(), wid = __builtin_amdgcn_readfirstlane(tid >> 6), lane = tid & 63, wr = wid >> 2, wc = wid & 3, fr = lane & 15, fq = lane >> 4;
;     unsigned voffA[2], voffB[2];
; #pragma unroll
;     for (int i = 0; i < 2; ++i) { int R, C; stage_rc(tid * 16 + i * 8192, R, C); const int r32 = Epi::PERM ? perm32(R & 31) : (R & 31);
;         const int Rb = Epi::ADJ ? 64 * (R >> 5) + r32 : (R & ~31) + r32;
;         voffA[i] = (unsigned)(R * (ABLK ? 64 : g.lda) + C) * 2u; voffB[i] = BBLK ? (unsigned)(R * 64 + C) * 2u : (unsigned)(Rb * g.ldb + C) * 2u; }
;     const size_t kstep = (size_t)(BK * 2);
;     const size_t hstepA = (size_t)HALF * (ABLK ? 64 : g.lda) * 2, hstepB = BBLK ? (size_t)16384 : (size_t)(Epi::ADJ ? 32 : HALF) * g.ldb * 2;
;     const size_t tstepB = BBLK ? ((size_t)g.ldb / 64) * 32768 : (size_t)BM * g.ldb * 2;
;     const size_t kstepB = BBLK ? (size_t)32768 : kstep;
;     auto b_k0 = [&](int k0) -> size_t { return BBLK ? (size_t)(k0 / BK) * 32768 : (size_t)k0 * 2; };
;     const unsigned ldsw = (unsigned)wid * 1024u;
;     const int aoff = lds_byte(wr * 64 + fr, fq * 8), boff = lds_byte(wc * 32 + fr, fq * 8);
;     ...
;     Unit cur, nxt; int ui = 0;
;     if (!S.next(0, cur)) return;
;     f32x4 acc[2][2][4][2];
; #pragma unroll
;     for (int a = 0; a < 2; ++a)
; #pragma unroll
;         for (int b = 0; b < 2; ++b)
; #pragma unroll
;             for (int m = 0; m < 4; ++m)
; #pragma unroll
;                 for (int n = 0; n < 2; ++n) acc[a][b][m][n] = (f32x4){0.f, 0.f, 0.f, 0.f};
;     bf16x8 At[4][2], B0[2][2], B1[2][2];
;     auto a_unit = [&](const Unit& u) -> const char* { return ABLK ? (const char*)g.A + (size_t)u.pm * ((size_t)g.lda / 64) * 32768 : (const char*)g.A + (size_t)u.pm * 2 * hstepA; };
;     auto a_tile = [&](const char* ub, int tau) -> const char* { return ub + (size_t)tau * (ABLK ? (size_t)32768 : kstep); };
;     const char* uA = a_unit(cur); int tbA = cur.k0 / BK;
;     const char* cA = a_tile(uA, tbA); const char* cB = (const char*)g.Bt + (size_t)cur.pn * tstepB + b_k0(cur.k0);
;     S.a_ready(cur);
;     if constexpr (SP2) {
.LBB0_2322:
	s_or_b64 exec, exec, s[2:3]
	v_mov_b32_e32 v4, v0
	s_waitcnt lgkmcnt(0)
	s_barrier
	s_add_u32 s46, s68, 0x14900000
	v_bfe_i32 v3, v4, 27, 1
	v_lshlrev_b32_e32 v1, 4, v4
	v_lshrrev_b32_e32 v3, 22, v3
	v_add_u32_e32 v3, v1, v3
	v_and_b32_e32 v3, 0xfffffc00, v3
	v_sub_u32_e32 v3, v1, v3
	v_lshrrev_b32_e32 v5, 4, v3
	v_bitop3_b32 v5, v5, v3, 32 bitop3:0x6c
	v_ashrrev_i32_e32 v3, 31, v3
	v_lshrrev_b32_e32 v3, 26, v3
	v_ashrrev_i32_e32 v2, 31, v4
	v_add_u32_e32 v3, v5, v3
	v_lshrrev_b32_e32 v2, 26, v2
	v_ashrrev_i32_e32 v3, 6, v3
	v_add_u32_e32 v2, v4, v2
	v_mul_i32_i24_e32 v8, 64, v3
	v_ashrrev_i32_e32 v2, 6, v2
	v_sub_u32_e32 v5, v5, v8
	v_mov_b32_e32 v8, 1
	v_lshlrev_b32_e32 v6, 3, v2
	v_lshlrev_b32_e32 v7, 5, v2
	v_ashrrev_i16_sdwa v5, v8, sext(v5) dst_sel:DWORD dst_unused:UNUSED_PAD src0_sel:DWORD src1_sel:BYTE_0
	v_and_b32_e32 v6, 0x1fffff0, v6
	v_and_b32_e32 v7, 32, v7
	v_bfe_i32 v5, v5, 0, 16
	v_add_u32_e32 v7, v7, v5
	v_add_lshl_u32 v6, v3, v6, 7
	v_add_u32_e32 v1, 0x2000, v1
	v_lshl_add_u32 v130, v7, 1, v6
	v_ashrrev_i32_e32 v6, 31, v1
	v_lshrrev_b32_e32 v6, 22, v6
	v_add_u32_e32 v6, v1, v6
	v_ashrrev_i32_e32 v6, 10, v6
	v_mul_i32_i24_e32 v7, 0x400, v6
	v_sub_u32_e32 v1, v1, v7
	v_lshrrev_b32_e32 v7, 4, v1
	v_bitop3_b32 v1, v7, v1, 32 bitop3:0x6c
	v_lshlrev_b32_e32 v7, 3, v6
	v_and_b32_e32 v9, 0x1fffff0, v7
	v_ashrrev_i32_e32 v7, 31, v1
	v_readfirstlane_b32 s2, v4
	v_lshrrev_b32_e32 v7, 26, v7
	s_addc_u32 s47, s69, 0
	s_ashr_i32 s4, s2, 6
	v_add_u32_e32 v10, v1, v7
	v_ashrrev_i32_e32 v7, 6, v10
	v_and_b32_e32 v10, 0xc0, v10
	s_ashr_i32 s3, s2, 8
	s_lshl_b32 s48, s4, 10
	v_readlane_b32 s5, v252, 16
	v_sub_u32_e32 v1, v1, v10
	s_add_u32 s38, s46, s5
	v_lshlrev_b32_e32 v11, 5, v6
	v_ashrrev_i16_sdwa v1, v8, sext(v1) dst_sel:DWORD dst_unused:UNUSED_PAD src0_sel:DWORD src1_sel:BYTE_0
	s_addc_u32 s39, s47, 0
	s_add_i32 s49, s48, 0
	v_and_b32_e32 v11, 32, v11
	v_bfe_i32 v8, v1, 0, 16
	s_add_i32 m0, s49, 0x10000
	v_add_u32_e32 v1, v11, v8
	v_add_lshl_u32 v9, v7, v9, 7
	global_load_lds_dwordx4 v130, s[38:39]
	s_add_i32 m0, s49, 0x12000
	v_lshl_add_u32 v132, v1, 1, v9
	s_add_u32 s6, s38, 0x4000
	global_load_lds_dwordx4 v132, s[38:39]
	s_addc_u32 s7, s39, 0
	s_add_i32 m0, s49, 0x14000
	v_mov_b32_e32 v131, 0
	global_load_lds_dwordx4 v130, s[6:7]
	s_add_i32 m0, s49, 0x16000
	s_mov_b32 s55, 0
	global_load_lds_dwordx4 v132, s[6:7]
	v_readlane_b32 s6, v252, 17
	v_readlane_b32 s7, v252, 18
	s_add_u32 s40, s1, s6
	s_addc_u32 s41, s33, s7
	s_add_i32 s50, s49, 0x2000
	s_mov_b32 m0, s49
	s_add_u32 s6, s40, 0x4000
	global_load_lds_dwordx4 v130, s[40:41]
	s_mov_b32 m0, s50
	s_addc_u32 s7, s41, 0
	s_add_i32 s51, s49, 0x4000
	global_load_lds_dwordx4 v132, s[40:41]
	s_mov_b32 m0, s51
	s_add_i32 s52, s49, 0x6000
	global_load_lds_dwordx4 v130, s[6:7]
	s_mov_b32 m0, s52
	s_cmp_eq_u32 s3, 1
	global_load_lds_dwordx4 v132, s[6:7]
	s_cselect_b64 s[10:11], -1, 0
	s_cmp_lg_u32 s3, 1
	v_mov_b32_e32 v133, v131
	s_cbranch_scc1 .LBB0_2324
	s_setprio 1
	s_barrier

; #define PG8_WAIT_V(n) asm volatile("s_waitcnt vmcnt(" #n ")" ::: "memory")
; #define PG8_BAR __builtin_amdgcn_s_barrier()
; template <class Epi, class Sched, bool ABLK = false, bool ALIGN_EPI = true, bool SP2 = true, bool BBLK = true>
; __device__ __forceinline__ void gemm_phase(LAS unsigned char* lds, const Gemm g, const Sched& S, const Epi& E) {
;     ...
;     PG8_WAIT_V(0);
;     if constexpr (!ALIGN_EPI) { if (wr == 0) PG8_BAR; }
;     PG8_BAR;
; __device__ __forceinline__ void xcd_barrier(const XcdBarrier& b) {
;     asm volatile("s_waitcnt vmcnt(0)" ::: "memory");
;     __syncthreads();
;     if (threadIdx.x == 0) {
;         unsigned* bar = b.bar;
;         __builtin_amdgcn_s_waitcnt(0);
;         unsigned nloc = b.st[0], nx = b.st[1];
;         if (nloc == 0u) { xcd_barrier_complete(bar, b.x, nloc, nx); b.st[0] = nloc; b.st[1] = nx; }
.LBB0_2334:
	s_waitcnt vmcnt(0)
	s_barrier
	s_waitcnt vmcnt(0)
	s_waitcnt vmcnt(0)
	s_setprio 0
	s_barrier
	s_and_saveexec_b64 s[2:3], s[92:93]
	s_cbranch_execz .LBB0_2386
	s_add_i32 s0, 0, 0x20000
	v_mov_b32_e32 v1, s0
	s_waitcnt vmcnt(0) expcnt(0) lgkmcnt(0)
	ds_read_b32 v3, v1
	s_add_i32 s0, 0, 0x20004
	v_mov_b32_e32 v1, s0
	ds_read_b32 v1, v1
	s_waitcnt lgkmcnt(1)
	v_cmp_ne_u32_e32 vcc, 0, v3
	s_cbranch_vccnz .LBB0_2350
	v_readlane_b32 s4, v252, 7
	v_readlane_b32 s5, v252, 8
	s_load_dwordx2 s[0:1], s[4:5], 0x4
	s_add_u32 s4, s68, 0x4200
	s_addc_u32 s5, s69, 0
	s_add_u32 s6, s68, 0x4400
	s_addc_u32 s7, s69, 0
	s_add_u32 s8, s68, 0x4500
	s_addc_u32 s9, s69, 0
	s_add_u32 s10, s68, 0x4600
	s_addc_u32 s11, s69, 0
	s_add_u32 s12, s68, 0x4700
	s_addc_u32 s13, s69, 0
	s_add_u32 s14, s68, 0x4800
	s_addc_u32 s15, s69, 0
	s_add_u32 s16, s68, 0x4900
	s_addc_u32 s17, s69, 0
	s_add_u32 s18, s68, 0x4a00
	s_addc_u32 s19, s69, 0
	s_add_u32 s20, s68, 0x4b00
	s_addc_u32 s21, s69, 0
	s_waitcnt lgkmcnt(0)
	s_mul_i32 s33, s0, s89
	s_add_u32 s0, s68, 0x4c00
	s_mul_i32 s33, s33, s1
	s_addc_u32 s1, s69, 0
	s_add_u32 s22, s68, 0x4d00
	s_addc_u32 s23, s69, 0
	s_add_u32 s24, s68, 0x4e00
	s_addc_u32 s25, s69, 0
	s_add_u32 s26, s68, 0x4f00
	s_addc_u32 s27, s69, 0
	s_add_u32 s28, s68, 0x5000
	s_addc_u32 s29, s69, 0
	s_add_u32 s30, s68, 0x5100
	s_addc_u32 s31, s69, 0
	s_add_u32 s34, s68, 0x5200
	s_addc_u32 s35, s69, 0
	s_add_u32 s36, s68, 0x5300
	s_addc_u32 s37, s69, 0
	s_mov_b32 s44, 1
	v_mov_b32_e32 v17, 0
	s_branch .LBB0_2338
